# SB loops: K/V fragment LDS addresses formed once per 64-key step in spare VGPRs instead of per tile body (19 fewer VALU per step)
# baseline (speedup 1.0000x reference)
; DEV int otid() { int t = threadIdx.x; asm volatile("" : "+v"(t)); return t; }
; DEV void sb_block(const Params& p, int item) {
;   const int tidx = otid();
;   const int wave = __builtin_amdgcn_readfirstlane(tidx >> 6), lane = tidx & 63, l31 = lane & 31, hh = lane >> 5;
;   const int qb = 7 - (item >> 6), bh = item & 63, b = bh >> 4, h = bh & 15;
;   const int qt = 8 * qb + wave;
;   const bf16_t* sq = (const bf16_t*)(p.ws + OFF_SQ);
;   const bf16_t* sk = (const bf16_t*)(p.ws + OFF_SK);
;   const bf16_t* svT = (const bf16_t*)(p.ws + OFF_SVT);
;   const bf16_t* ssg = (const bf16_t*)(p.ws + OFF_SSG);
;   bf16_t* ob = (bf16_t*)(p.ws + OFF_OB);
;   const size_t row0 = (size_t)b * 2048;
;   bf16x8 qf[8];
;   {
;     const bf16_t* qp = sq + (row0 + qt * 32 + l31) * 2048 + h * 128 + 8 * hh;
; #pragma unroll
;     for (int s = 0; s < 8; ++s) qf[s] = ld16(qp + 16 * s);
;   }
;   f32x16 O[4];
; #pragma unroll
;   for (int d = 0; d < 4; ++d) for (int g = 0; g < 16; ++g) O[d][g] = 0.f;
;   float accp = 1.f;
;   const bf16_t* ksrc = sk + (row0 + (lane >> 4)) * 2048 + h * 128;
;   const bf16_t* vsrc = svT + ((size_t)(b * 2048 + h * 128 + (lane >> 3))) * 2048;
;     ...
;   const int KO0 = l31 * 256 + ((hh ^ (l31 & 15)) * 16);
;   const int VO0 = 16384 + l31 * 128 + ((hh ^ ((l31 >> 1) & 7)) * 16);
;   const int nsteps = 4 * qb + 4;
;   asm volatile("s_waitcnt vmcnt(0)" ::: "memory");
;   __syncthreads();
;   { const int j0 = nsteps - 1; SB_DMA(j0, 0); SB_DMA((j0 > 0 ? j0 - 1 : 0), 1); SB_DMA((j0 > 1 ? j0 - 2 : 0), 2); }
.LBB0_541:
	v_lshlrev_b32_e32 v3, 8, v203
	v_xor_b32_e32 v5, v202, v14
	v_lshl_or_b32 v205, v5, 4, v3
	v_lshrrev_b32_e32 v5, 1, v201
	v_bitop3_b32 v5, v202, v5, 7 bitop3:0x78
	s_lshl_b32 s10, s10, 10
	v_lshlrev_b32_e32 v3, 7, v203
	v_lshlrev_b32_e32 v5, 4, v5
	s_movk_i32 s11, 0x4000
	s_add_i32 s10, s10, s1
	v_or3_b32 v206, v5, v3, s11
	v_add_u32_e32 v3, s10, v12
	v_mov_b32_e32 v5, v177
	v_readfirstlane_b32 s1, v3
	v_lshl_add_u64 v[4:5], v[4:5], 1, v[8:9]
	s_mov_b32 m0, s1
	v_lshlrev_b32_e32 v3, 2, v202
	global_load_lds_dwordx4 v[4:5], off
	v_or_b32_e32 v4, 1, v3
	v_cmp_lt_u32_e64 s[14:15], v4, v203
	v_or_b32_e32 v4, 2, v3
	v_cmp_lt_u32_e64 s[16:17], v4, v203
	v_or_b32_e32 v4, 3, v3
	v_cmp_lt_u32_e64 s[18:19], v4, v203
	v_or_b32_e32 v4, 8, v3
	v_cmp_lt_u32_e64 s[20:21], v4, v203
	v_or_b32_e32 v4, 9, v3
	v_cmp_lt_u32_e64 s[22:23], v4, v203
	v_or_b32_e32 v4, 10, v3
	v_cmp_lt_u32_e64 s[24:25], v4, v203
	v_or_b32_e32 v4, 11, v3
	v_cmp_lt_u32_e64 s[26:27], v4, v203
	v_or_b32_e32 v4, 16, v3
	v_cmp_lt_u32_e64 s[28:29], v4, v203
	v_or_b32_e32 v4, 17, v3
	v_cmp_lt_u32_e64 s[30:31], v4, v203
	v_or_b32_e32 v4, 18, v3
	v_cmp_lt_u32_e64 s[34:35], v4, v203
	v_or_b32_e32 v4, 19, v3
	v_cmp_lt_u32_e64 s[36:37], v4, v203
	v_or_b32_e32 v4, 24, v3
	s_add_i32 s1, s33, -16
	v_cmp_lt_u32_e64 s[38:39], v4, v203
	v_or_b32_e32 v4, 25, v3
	s_lshl_b32 s92, s1, 3
	v_cmp_lt_u32_e64 s[12:13], v3, v203
	v_cmp_lt_u32_e64 s[40:41], v4, v203
	v_or_b32_e32 v4, 26, v3
	v_or_b32_e32 v3, 27, v3
	s_lshl_b64 s[70:71], s[92:93], 12
	v_cmp_lt_u32_e64 s[44:45], v3, v203
	v_or_b32_e32 v3, s92, v10
	v_writelane_b32 v252, s70, 7
	v_lshrrev_b32_e32 v3, 1, v3
	s_lshl_b32 s3, s1, 10
	v_writelane_b32 v252, s71, 8
	s_lshl_b32 s1, s89, 4
	v_xor_b32_e32 v3, v3, v201
	v_writelane_b32 v252, s1, 9
	s_lshl_b32 s1, s89, 12
	v_lshlrev_b32_e32 v3, 3, v3
	v_writelane_b32 v252, s1, 10
	s_add_i32 s1, s33, -15
	v_and_b32_e32 v16, 56, v3
	v_mov_b32_e32 v3, v177
	s_lshl_b32 s92, s1, 3
	v_lshl_add_u64 v[184:185], v[0:1], 0, v[2:3]
	v_or_b32_e32 v2, s92, v10
	v_lshrrev_b32_e32 v2, 1, v2
	v_xor_b32_e32 v2, v2, v201
	s_add_i32 s33, s33, -14
	s_lshl_b64 s[70:71], s[92:93], 12
	v_lshlrev_b32_e32 v2, 3, v2
	s_lshl_b32 s92, s33, 3
	v_and_b32_e32 v18, 56, v2
	v_or_b32_e32 v2, s92, v10
	v_lshrrev_b32_e32 v2, 1, v2
	v_xor_b32_e32 v2, v2, v201
	v_lshlrev_b32_e32 v176, 4, v13
	v_lshlrev_b32_e32 v2, 3, v2
	v_writelane_b32 v252, s70, 11
	v_lshl_add_u64 v[186:187], v[0:1], 0, v[176:177]
	v_and_b32_e32 v20, 56, v2
	v_lshlrev_b32_e32 v176, 4, v15
	v_mov_b32_e32 v7, v177
	v_mov_b32_e32 v14, v177
	v_mov_b32_e32 v15, v177
	v_cmp_gt_u32_e64 s[10:11], 32, v11
	v_cmp_lt_u32_e64 s[42:43], v4, v203
	v_writelane_b32 v252, s71, 12
	v_lshl_add_u64 v[188:189], v[0:1], 0, v[176:177]
	v_lshl_add_u64 v[190:191], v[6:7], 1, v[0:1]
	v_mov_b32_e32 v0, v177
	v_mov_b32_e32 v1, v177
	v_mov_b32_e32 v2, v177
	v_mov_b32_e32 v4, v177
	v_mov_b32_e32 v5, v177
	v_mov_b32_e32 v6, v177
	v_mov_b32_e32 v8, v177
	v_mov_b32_e32 v9, v177
	v_mov_b32_e32 v10, v177
	v_mov_b32_e32 v11, v177
	v_mov_b32_e32 v12, v177
	v_mov_b32_e32 v13, v177
	v_lshlrev_b32_e32 v176, 1, v16
	v_lshlrev_b32_e32 v192, 1, v18
	v_lshlrev_b32_e32 v194, 1, v20
	v_mov_b64_e32 v[30:31], v[14:15]
	v_mov_b64_e32 v[46:47], v[14:15]
	v_mov_b64_e32 v[62:63], v[14:15]
	s_lshl_b32 s79, s1, 10
	s_lshl_b32 s68, s64, 2
	s_lshl_b32 s84, s64, 10
	s_lshl_b64 s[64:65], s[92:93], 12
	s_lshl_b32 s85, s33, 10
	s_lshl_b32 s76, s66, 2
	s_lshl_b32 s70, s66, 10
	v_mov_b32_e32 v183, v177
	s_lshl_b32 s86, s69, 10
	s_lshl_b32 s87, s67, 10
	s_add_i32 s88, s89, -6
	v_writelane_b32 v252, s89, 13
	s_add_i32 s89, s89, -7
	s_add_i32 s71, s0, 3
	v_mov_b32_e32 v197, 1.0
	s_mov_b32 s33, 0
	s_mov_b32 s69, 0
	v_mov_b64_e32 v[28:29], v[12:13]
	v_mov_b64_e32 v[26:27], v[10:11]
	v_mov_b64_e32 v[24:25], v[8:9]
	v_mov_b64_e32 v[22:23], v[6:7]
	v_mov_b64_e32 v[20:21], v[4:5]
	v_mov_b64_e32 v[18:19], v[2:3]
	v_mov_b64_e32 v[16:17], v[0:1]
	v_mov_b64_e32 v[44:45], v[12:13]
	v_mov_b64_e32 v[42:43], v[10:11]
	v_mov_b64_e32 v[40:41], v[8:9]
	v_mov_b64_e32 v[38:39], v[6:7]
	v_mov_b64_e32 v[36:37], v[4:5]
	v_mov_b64_e32 v[34:35], v[2:3]
	v_mov_b64_e32 v[32:33], v[0:1]
	v_mov_b64_e32 v[60:61], v[12:13]
	v_mov_b64_e32 v[58:59], v[10:11]
	v_mov_b64_e32 v[56:57], v[8:9]
	v_mov_b64_e32 v[54:55], v[6:7]
	v_mov_b64_e32 v[52:53], v[4:5]
	v_mov_b64_e32 v[50:51], v[2:3]
	v_mov_b64_e32 v[48:49], v[0:1]
	s_waitcnt vmcnt(0)
	v_mov_b32_e32 v228, v205
	v_xor_b32_e32 v229, 32, v205
	v_xor_b32_e32 v230, 64, v205
	v_xor_b32_e32 v231, 0x60, v205
	v_xor_b32_e32 v232, 0x80, v205
	v_xor_b32_e32 v233, 0xa0, v205
	v_xor_b32_e32 v234, 0xc0, v205
	v_xor_b32_e32 v235, 0xe0, v205
	v_mov_b32_e32 v236, v206
	v_xor_b32_e32 v237, 32, v206
	v_xor_b32_e32 v238, 64, v206
	v_xor_b32_e32 v239, 0x60, v206
	s_branch .LBB0_543

; DEV void sb_block(const Params& p, int item) {
;     ...
;   for (int n = 0; n < nsteps; ++n) {
;     const int j = nsteps - 1 - n, buf = n & 3;
;     asm volatile("s_waitcnt vmcnt(8)" ::: "memory");
;     __builtin_amdgcn_s_barrier();
;     asm volatile("" ::: "memory");
;     { const int jn = j > 3 ? j - 3 : 0; SB_DMA(jn, (n + 3) & 3); }
;     const char* lb_ = smem + buf * 32768;
;     int ko0 = KO0, vo0 = VO0;
;     asm volatile("" : "+v"(ko0), "+v"(vo0));
;     if (2 * j + 1 == qt) sb_tile<true>(lb_ + 32 * 256, lb_, ko0, vo0 ^ 64, qf, O, accp, l31, hh);
;     else if (2 * j + 1 < qt) sb_tile<false>(lb_ + 32 * 256, lb_, ko0, vo0 ^ 64, qf, O, accp, l31, hh);
.LBB0_559:
	s_and_b32 s0, s33, 0x18000
	s_add_i32 s92, s0, 0
	v_add_u32_e32 v240, s92, v228
	v_add_u32_e32 v241, s92, v229
	v_add_u32_e32 v242, s92, v230
	v_add_u32_e32 v243, s92, v231
	v_add_u32_e32 v244, s92, v232
	v_add_u32_e32 v245, s92, v233
	v_add_u32_e32 v246, s92, v234
	v_add_u32_e32 v247, s92, v235
	v_add_u32_e32 v248, s92, v236
	v_add_u32_e32 v249, s92, v237
	v_add_u32_e32 v250, s92, v238
	v_add_u32_e32 v251, s92, v239
	s_add_i32 s0, s74, s69
	v_mov_b32_e32 v168, v205
	v_mov_b32_e32 v193, v206
	s_cmp_lg_u32 s89, s69
	s_mov_b64 s[66:67], -1
	s_cbranch_scc0 .LBB0_563
	s_add_i32 s1, s0, 7
	s_cmp_ge_i32 s1, s75
	s_cbranch_scc1 .Lsb_skip_A0
; DEV f32x16 mfma32(bf16x8 a, bf16x8 b, f32x16 c) { return __builtin_amdgcn_mfma_f32_32x32x16_bf16(a, b, c, 0, 0, 0); }
; template <bool DIAG>
; DEV void sb_tile(const char* lk, const char* lv, const int ko0, const int vo0, const bf16x8 (&qf)[8], f32x16 (&O)[4], float& accp,
;                  const int l31, const int hh) {
;   f32x16 z;
;   for (int g = 0; g < 16; ++g) z[g] = 0.f;
;   {
;     bf16x8 kf[8];
; #pragma unroll
;     for (int s = 0; s < 8; ++s) kf[s] = *(const bf16x8*)(lk + (ko0 ^ (32 * s)));
;     __builtin_amdgcn_sched_barrier(0);
; #pragma unroll
;     for (int s = 0; s < 8; ++s) z = mfma32(kf[s], qf[s], z);
;   }
;   bf16x8 vf[4][2];
; #pragma unroll
;   for (int d = 0; d < 4; ++d) { vf[d][0] = *(const bf16x8*)(lv + d * 4096 + vo0); vf[d][1] = *(const bf16x8*)(lv + d * 4096 + (vo0 ^ 32)); }
;   __builtin_amdgcn_sched_barrier(0);
;   float be[16], om[16];
; #pragma unroll
;   for (int g = 0; g < 16; ++g) {
;     const float e = __builtin_amdgcn_exp2f(fminf(-z[g], 120.f));
;     be[g] = __builtin_amdgcn_rcpf(1.f + e);
;     om[g] = e * be[g];
;     if (DIAG) { const int kl = (g & 3) + 8 * (g >> 2) + 4 * hh; if (kl >= l31) { be[g] = 0.f; om[g] = 1.f; } }
;   }
;   float gp[4], pp[4], tot[4];
; #pragma unroll
;   for (int q = 0; q < 4; ++q) { gp[q] = (om[4 * q] * om[4 * q + 1]) * (om[4 * q + 2] * om[4 * q + 3]); pp[q] = __shfl_xor(gp[q], 32); tot[q] = gp[q] * pp[q]; }
;   float suf[4];
;   suf[3] = accp; suf[2] = suf[3] * tot[3]; suf[1] = suf[2] * tot[2]; suf[0] = suf[1] * tot[1];
;   accp = suf[0] * tot[0];
;   f32x16 w;
; #pragma unroll
;   for (int q = 0; q < 4; ++q) {
;     float a = suf[q] * (hh == 0 ? pp[q] : 1.f);
;     w[4 * q + 3] = be[4 * q + 3] * a; a *= om[4 * q + 3];
;     w[4 * q + 2] = be[4 * q + 2] * a; a *= om[4 * q + 2];
;     w[4 * q + 1] = be[4 * q + 1] * a; a *= om[4 * q + 1];
;     w[4 * q + 0] = be[4 * q + 0] * a;
;   }
;   const bf16x8 w0 = cvt8<0>(w), w1 = cvt8<1>(w);
; #pragma unroll
;   for (int d = 0; d < 4; ++d) { O[d] = mfma32(vf[d][0], w0, O[d]); O[d] = mfma32(vf[d][1], w1, O[d]); }
	ds_read_b128 v[64:67], v240 offset:8192
	ds_read_b128 v[80:83], v241 offset:8192
	ds_read_b128 v[84:87], v242 offset:8192
	ds_read_b128 v[88:91], v243 offset:8192
	ds_read_b128 v[92:95], v244 offset:8192
	ds_read_b128 v[96:99], v245 offset:8192
	ds_read_b128 v[100:103], v246 offset:8192
	ds_read_b128 v[104:107], v247 offset:8192
	s_waitcnt lgkmcnt(0)
	v_mfma_f32_32x32x16_bf16 v[64:79], v[64:67], v[128:131], 0
	v_mfma_f32_32x32x16_bf16 v[64:79], v[80:83], v[132:135], v[64:79]
	v_mfma_f32_32x32x16_bf16 v[64:79], v[84:87], v[136:139], v[64:79]
	v_mfma_f32_32x32x16_bf16 v[64:79], v[88:91], v[140:143], v[64:79]
	v_mfma_f32_32x32x16_bf16 v[64:79], v[92:95], v[144:147], v[64:79]
	v_mfma_f32_32x32x16_bf16 v[64:79], v[96:99], v[148:151], v[64:79]
	v_mfma_f32_32x32x16_bf16 v[64:79], v[100:103], v[152:155], v[64:79]
	ds_read_b128 v[84:87], v250
	ds_read_b128 v[96:99], v250 offset:4096
	ds_read_b128 v[80:83], v251
	ds_read_b128 v[100:103], v251 offset:4096
	ds_read_b128 v[112:115], v250 offset:8192
	ds_read_b128 v[164:167], v250 offset:12288
	ds_read_b128 v[116:119], v251 offset:8192
	ds_read_b128 v[160:163], v251 offset:12288
	v_mfma_f32_32x32x16_bf16 v[64:79], v[104:107], v[156:159], v[64:79]
	s_nop 11
	v_min_f32_e64 v68, -v68, s32
	v_exp_f32_e32 v90, v68
	v_min_f32_e64 v68, -v69, s32
	v_exp_f32_e32 v91, v68
	v_add_f32_e32 v68, 1.0, v90
	v_min_f32_e64 v73, -v73, s32
	v_add_f32_e32 v69, 1.0, v91
	v_rcp_f32_e32 v68, v68
	v_rcp_f32_e32 v69, v69
	v_exp_f32_e32 v104, v73
	v_max_f32_e64 v73, -v74, -v74
	v_max_f32_e64 v74, -v75, -v75
	v_min_f32_e64 v72, -v72, s32
	v_min_f32_e32 v74, 0x42f00000, v74
	v_min_f32_e64 v75, -v77, s32
	v_max_f32_e64 v77, -v79, -v79
	v_and_b32_e32 v79, 64, v219
	v_exp_f32_e32 v72, v72
	v_exp_f32_e32 v105, v74
	v_max_f32_e64 v74, -v76, -v76
	v_exp_f32_e32 v76, v75
	v_max_f32_e64 v75, -v78, -v78
	v_xor_b32_e32 v78, 32, v219
	v_add_u32_e32 v79, 64, v79
	v_min_f32_e32 v73, 0x42f00000, v73
	v_cmp_lt_i32_e32 vcc, v78, v79
	v_pk_mul_f32 v[90:91], v[90:91], v[68:69]
	v_exp_f32_e32 v73, v73
	v_cndmask_b32_e32 v78, v219, v78, vcc
	v_lshlrev_b32_e32 v170, 2, v78
	v_pk_mul_f32 v[78:79], v[90:91], v[90:91] op_sel_hi:[0,1]
	v_add_f32_e32 v78, 1.0, v72
	v_rcp_f32_e32 v108, v78
	v_add_f32_e32 v78, 1.0, v104
	v_rcp_f32_e32 v110, v78
	v_add_f32_e32 v78, 1.0, v73
	v_rcp_f32_e32 v109, v78
	v_add_f32_e32 v78, 1.0, v105
	v_min_f32_e32 v74, 0x42f00000, v74
	v_rcp_f32_e32 v111, v78
	v_exp_f32_e32 v74, v74
	v_min_f32_e32 v75, 0x42f00000, v75
	v_exp_f32_e32 v75, v75
	v_min_f32_e32 v77, 0x42f00000, v77
	v_exp_f32_e32 v77, v77
	v_pk_mul_f32 v[72:73], v[72:73], v[108:109]
	v_pk_mul_f32 v[104:105], v[104:105], v[110:111]
	v_pk_mul_f32 v[120:121], v[72:73], v[104:105]
	v_add_f32_e32 v72, 1.0, v74
	v_rcp_f32_e32 v122, v72
	v_add_f32_e32 v72, 1.0, v76
	v_rcp_f32_e32 v124, v72
	v_add_f32_e32 v72, 1.0, v75
	v_min_f32_e64 v70, -v70, s32
	v_rcp_f32_e32 v123, v72
	v_add_f32_e32 v72, 1.0, v77
	v_exp_f32_e32 v92, v70
	v_rcp_f32_e32 v125, v72
	v_min_f32_e64 v70, -v71, s32
	v_min_f32_e64 v67, -v67, s32
	v_exp_f32_e32 v93, v70
	v_min_f32_e64 v64, -v64, s32
	v_exp_f32_e32 v196, v67
	v_exp_f32_e32 v88, v64
	v_pk_mul_f32 v[74:75], v[74:75], v[122:123]
	v_pk_mul_f32 v[76:77], v[76:77], v[124:125]
	v_add_f32_e32 v70, 1.0, v92
	v_pk_mul_f32 v[126:127], v[74:75], v[76:77]
	v_add_f32_e32 v71, 1.0, v93
	v_mul_f32_e32 v72, v126, v127
	v_add_f32_e32 v67, 1.0, v196
	v_rcp_f32_e32 v70, v70
	v_rcp_f32_e32 v71, v71
	v_pk_mul_f32 v[120:121], v[120:121], v[120:121] op_sel:[0,1] op_sel_hi:[1,0]
	v_mov_b32_e32 v74, v72
	s_nop 1
	v_permlane32_swap_b32_e32 v72, v74
	v_add_f32_e32 v64, 1.0, v88
	v_min_f32_e64 v66, -v66, s32
	v_rcp_f32_e32 v67, v67
	v_mov_b32_e32 v121, v120
	s_nop 1
	v_permlane32_swap_b32_e32 v120, v121
	v_rcp_f32_e32 v64, v64
	v_min_f32_e64 v65, -v65, s32
	v_exp_f32_e32 v94, v66
	v_exp_f32_e32 v169, v65
	v_pk_mul_f32 v[92:93], v[92:93], v[70:71]
	s_waitcnt lgkmcnt(0)
	v_mul_f32_e32 v127, v72, v74
	v_pk_mul_f32 v[106:107], v[92:93], v[92:93] op_sel_hi:[0,1]
	v_mov_b32_e32 v126, v67
	v_add_f32_e32 v66, 1.0, v94
	v_mov_b32_e32 v89, v79
	v_cndmask_b32_e64 v72, 1.0, v121, s[10:11]
	v_mov_b32_e32 v78, v109
	v_mov_b32_e32 v79, v111
	v_mov_b32_e32 v109, v110
	v_pk_mul_f32 v[110:111], v[196:197], v[126:127]
	v_mov_b32_e32 v106, v64
	v_add_f32_e32 v65, 1.0, v169
	v_rcp_f32_e32 v66, v66
	v_mul_f32_e32 v127, v72, v111
	v_pk_mul_f32 v[88:89], v[88:89], v[106:107]
	v_rcp_f32_e32 v65, v65
	v_mul_f32_e32 v126, v105, v127
	v_mov_b32_e32 v105, v89
	s_nop 1
	v_permlane32_swap_b32_e32 v89, v105
	v_mov_b32_e32 v95, v120
	v_mov_b32_e32 v120, v66
	v_mul_f32_e32 v73, v73, v126
	v_pk_mul_f32 v[94:95], v[94:95], v[120:121]
	v_mul_f32_e32 v72, v104, v73
	v_mul_f32_e32 v104, v169, v65
	v_pk_mul_f32 v[120:121], v[94:95], v[110:111]
	s_waitcnt lgkmcnt(0)
	v_pk_mul_f32 v[88:89], v[88:89], v[104:105]
	v_cndmask_b32_e64 v90, 1.0, v105, s[10:11]
	v_pk_mul_f32 v[88:89], v[88:89], v[120:121]
	v_mov_b32_e32 v95, v88
	s_nop 1
	v_permlane32_swap_b32_e32 v88, v95
	v_cndmask_b32_e64 v74, 1.0, v74, s[10:11]
	v_pk_mul_f32 v[78:79], v[78:79], v[126:127]
	v_pk_mul_f32 v[72:73], v[108:109], v[72:73]
	v_cvt_pk_bf16_f32 v209, v78, v79
	s_waitcnt lgkmcnt(0)
	v_mul_f32_e32 v88, v88, v95
	v_mul_f32_e32 v199, v88, v89
	v_cndmask_b32_e64 v88, 1.0, v95, s[10:11]
	v_mul_f32_e32 v89, v88, v89
	v_mul_f32_e32 v88, v110, v89
	v_pk_mul_f32 v[66:67], v[66:67], v[88:89]
	v_mul_f32_e32 v89, v90, v121
	v_mul_f32_e32 v95, v94, v88
	v_mul_f32_e32 v88, v93, v89
	v_mul_f32_e32 v93, v92, v88
	v_mul_f32_e32 v92, v91, v93
	v_mul_f32_e32 v91, v197, v74
	v_mul_f32_e32 v90, v77, v91
	v_mul_f32_e32 v94, v104, v95
	v_mul_f32_e32 v75, v75, v90
	v_pk_mul_f32 v[64:65], v[64:65], v[94:95]
	v_pk_mul_f32 v[68:69], v[68:69], v[92:93]
	v_pk_mul_f32 v[70:71], v[70:71], v[88:89]
	v_mov_b32_e32 v88, v123
	v_mov_b32_e32 v123, v124
	v_mul_f32_e32 v74, v76, v75
	v_pk_mul_f32 v[74:75], v[122:123], v[74:75]
	v_cvt_pk_bf16_f32 v170, v64, v65
	v_cvt_pk_bf16_f32 v171, v66, v67
	v_cvt_pk_bf16_f32 v172, v68, v69
	v_cvt_pk_bf16_f32 v173, v70, v71
	v_cvt_pk_bf16_f32 v208, v72, v73
	v_cvt_pk_bf16_f32 v210, v74, v75
	v_mfma_f32_32x32x16_bf16 v[64:79], v[84:87], v[170:173], v[48:63]
	v_mov_b32_e32 v89, v125
	v_mul_f32_e64 v88, v88, v90
	v_mul_f32_e64 v89, v89, v91
	v_cvt_pk_bf16_f32 v211, v88, v89
	s_nop 1
	v_mfma_f32_32x32x16_bf16 v[64:79], v[80:83], v[208:211], v[64:79]
	v_mfma_f32_32x32x16_bf16 v[80:95], v[96:99], v[170:173], v[32:47]
	v_mfma_f32_32x32x16_bf16 v[80:95], v[100:103], v[208:211], v[80:95]
	v_mfma_f32_32x32x16_bf16 v[96:111], v[112:115], v[170:173], v[16:31]
	v_mfma_f32_32x32x16_bf16 v[96:111], v[116:119], v[208:211], v[96:111]
	v_mfma_f32_32x32x16_bf16 v[112:127], v[164:167], v[170:173], v[0:15]
	v_mfma_f32_32x32x16_bf16 v[112:127], v[160:163], v[208:211], v[112:127]

; DEV f32x16 mfma32(bf16x8 a, bf16x8 b, f32x16 c) { return __builtin_amdgcn_mfma_f32_32x32x16_bf16(a, b, c, 0, 0, 0); }
; template <bool DIAG>
; DEV void sb_tile(const char* lk, const char* lv, const int ko0, const int vo0, const bf16x8 (&qf)[8], f32x16 (&O)[4], float& accp,
;                  const int l31, const int hh) {
;   f32x16 z;
;   for (int g = 0; g < 16; ++g) z[g] = 0.f;
;   {
;     bf16x8 kf[8];
; #pragma unroll
;     for (int s = 0; s < 8; ++s) kf[s] = *(const bf16x8*)(lk + (ko0 ^ (32 * s)));
;     __builtin_amdgcn_sched_barrier(0);
; #pragma unroll
;     for (int s = 0; s < 8; ++s) z = mfma32(kf[s], qf[s], z);
;   }
;   bf16x8 vf[4][2];
; #pragma unroll
;   for (int d = 0; d < 4; ++d) { vf[d][0] = *(const bf16x8*)(lv + d * 4096 + vo0); vf[d][1] = *(const bf16x8*)(lv + d * 4096 + (vo0 ^ 32)); }
;   __builtin_amdgcn_sched_barrier(0);
;   float be[16], om[16];
; #pragma unroll
;   for (int g = 0; g < 16; ++g) {
;     const float e = __builtin_amdgcn_exp2f(fminf(-z[g], 120.f));
;     be[g] = __builtin_amdgcn_rcpf(1.f + e);
;     om[g] = e * be[g];
;     if (DIAG) { const int kl = (g & 3) + 8 * (g >> 2) + 4 * hh; if (kl >= l31) { be[g] = 0.f; om[g] = 1.f; } }
;   }
;   float gp[4], pp[4], tot[4];
; #pragma unroll
;   for (int q = 0; q < 4; ++q) { gp[q] = (om[4 * q] * om[4 * q + 1]) * (om[4 * q + 2] * om[4 * q + 3]); pp[q] = __shfl_xor(gp[q], 32); tot[q] = gp[q] * pp[q]; }
;   float suf[4];
;   suf[3] = accp; suf[2] = suf[3] * tot[3]; suf[1] = suf[2] * tot[2]; suf[0] = suf[1] * tot[1];
;   accp = suf[0] * tot[0];
;   f32x16 w;
; #pragma unroll
;   for (int q = 0; q < 4; ++q) {
;     float a = suf[q] * (hh == 0 ? pp[q] : 1.f);
.LBB0_563:
	s_andn2_b64 vcc, exec, s[66:67]
	s_cbranch_vccnz .LBB0_565
	ds_read_b128 v[64:67], v240 offset:8192
	ds_read_b128 v[80:83], v241 offset:8192
	ds_read_b128 v[84:87], v242 offset:8192
	ds_read_b128 v[88:91], v243 offset:8192
	ds_read_b128 v[92:95], v244 offset:8192
	ds_read_b128 v[96:99], v245 offset:8192
	ds_read_b128 v[100:103], v246 offset:8192
	ds_read_b128 v[112:115], v247 offset:8192
	s_waitcnt lgkmcnt(0)
	v_mfma_f32_32x32x16_bf16 v[64:79], v[64:67], v[128:131], 0
	v_mfma_f32_32x32x16_bf16 v[64:79], v[80:83], v[132:135], v[64:79]
	v_mfma_f32_32x32x16_bf16 v[64:79], v[84:87], v[136:139], v[64:79]
	v_mfma_f32_32x32x16_bf16 v[64:79], v[88:91], v[140:143], v[64:79]
	v_mfma_f32_32x32x16_bf16 v[64:79], v[92:95], v[144:147], v[64:79]
	v_mfma_f32_32x32x16_bf16 v[64:79], v[96:99], v[148:151], v[64:79]
	v_mfma_f32_32x32x16_bf16 v[64:79], v[100:103], v[152:155], v[64:79]
	ds_read_b128 v[108:111], v250
	ds_read_b128 v[96:99], v250 offset:4096
	ds_read_b128 v[104:107], v251
	ds_read_b128 v[100:103], v251 offset:4096
	ds_read_b128 v[88:91], v250 offset:8192
	ds_read_b128 v[84:87], v250 offset:12288
	ds_read_b128 v[92:95], v251 offset:8192
	ds_read_b128 v[80:83], v251 offset:12288
	v_mfma_f32_32x32x16_bf16 v[64:79], v[112:115], v[156:159], v[64:79]
	s_nop 11
	v_min_f32_e64 v64, -v64, s32
	v_exp_f32_e32 v64, v64
	v_min_f32_e64 v65, -v65, s32
	v_exp_f32_e32 v65, v65
	v_add_f32_e32 v112, 1.0, v64
	v_rcp_f32_e32 v120, v112
	v_add_f32_e32 v112, 1.0, v65
	v_min_f32_e64 v66, -v66, s32
	v_rcp_f32_e32 v121, v112
	v_exp_f32_e32 v112, v66
	v_min_f32_e64 v66, -v67, s32
	v_exp_f32_e32 v67, v66
	v_add_f32_e32 v66, 1.0, v112
	v_rcp_f32_e32 v122, v66
	v_mul_f32_e32 v65, v65, v121
	v_add_f32_e32 v66, 1.0, v67
	v_rcp_f32_e32 v123, v66
	v_cndmask_b32_e64 v66, 1.0, v65, s[14:15]
	v_mul_f32_e32 v65, v112, v122
	v_cndmask_b32_e64 v112, 1.0, v65, s[16:17]
	v_mul_f32_e32 v65, v67, v123
	v_min_f32_e64 v67, -v68, s32
	v_exp_f32_e32 v67, v67
	v_min_f32_e64 v68, -v69, s32
	v_exp_f32_e32 v69, v68
	v_cndmask_b32_e64 v68, 1.0, v65, s[18:19]
	v_add_f32_e32 v65, 1.0, v67
	v_rcp_f32_e32 v124, v65
	v_add_f32_e32 v65, 1.0, v69
	v_rcp_f32_e32 v125, v65
	v_min_f32_e64 v65, -v70, s32
	v_exp_f32_e32 v65, v65
	v_mul_f32_e32 v67, v67, v124
	v_cndmask_b32_e64 v70, 1.0, v67, s[20:21]
	v_mul_f32_e32 v67, v69, v125
	v_add_f32_e32 v69, 1.0, v65
	v_rcp_f32_e32 v126, v69
	v_min_f32_e64 v69, -v71, s32
	v_exp_f32_e32 v69, v69
	v_mul_f32_e32 v65, v65, v126
	v_cndmask_b32_e64 v115, 1.0, v65, s[24:25]
	v_cndmask_b32_e64 v114, 1.0, v67, s[22:23]
	v_add_f32_e32 v65, 1.0, v69
	v_rcp_f32_e32 v127, v65
	v_min_f32_e64 v65, -v72, s32
	v_exp_f32_e32 v65, v65
	v_min_f32_e64 v67, -v73, s32
	v_exp_f32_e32 v67, v67
	v_mul_f32_e32 v69, v69, v127
	v_add_f32_e32 v71, 1.0, v65
	v_rcp_f32_e32 v160, v71
	v_add_f32_e32 v71, 1.0, v67
	v_rcp_f32_e32 v161, v71
	v_cndmask_b32_e64 v71, 1.0, v69, s[26:27]
	v_mul_f32_e32 v65, v65, v160
	v_cndmask_b32_e64 v72, 1.0, v65, s[28:29]
	v_mul_f32_e32 v65, v67, v161
	v_min_f32_e64 v67, -v74, s32
	v_exp_f32_e32 v67, v67
	v_min_f32_e64 v69, -v75, s32
	v_exp_f32_e32 v69, v69
	v_cndmask_b32_e64 v74, 1.0, v65, s[30:31]
	v_add_f32_e32 v65, 1.0, v67
	v_rcp_f32_e32 v162, v65
	v_add_f32_e32 v65, 1.0, v69
	v_rcp_f32_e32 v163, v65
	v_min_f32_e64 v65, -v76, s32
	v_exp_f32_e32 v65, v65
	v_mul_f32_e32 v67, v67, v162
	v_cndmask_b32_e64 v75, 1.0, v67, s[34:35]
	v_mul_f32_e32 v67, v69, v163
	v_add_f32_e32 v69, 1.0, v65
	v_rcp_f32_e32 v164, v69
	v_min_f32_e64 v69, -v77, s32
	v_exp_f32_e32 v69, v69
	v_mul_f32_e32 v65, v65, v164
	v_cndmask_b32_e64 v76, 1.0, v65, s[38:39]
	v_cndmask_b32_e64 v73, 1.0, v67, s[36:37]
	v_add_f32_e32 v65, 1.0, v69
	v_rcp_f32_e32 v165, v65
	v_min_f32_e64 v65, -v78, s32
	v_exp_f32_e32 v65, v65
	v_min_f32_e64 v67, -v79, s32
	v_exp_f32_e32 v67, v67
	v_mul_f32_e32 v69, v69, v165
	v_add_f32_e32 v77, 1.0, v65
	v_rcp_f32_e32 v166, v77
	v_add_f32_e32 v77, 1.0, v67
	v_rcp_f32_e32 v167, v77
	v_cndmask_b32_e64 v78, 1.0, v69, s[40:41]
	v_mul_f32_e32 v65, v65, v166
	v_cndmask_b32_e64 v79, 1.0, v65, s[42:43]
	v_mul_f32_e32 v65, v67, v167
	v_and_b32_e32 v67, 64, v219
	v_cndmask_b32_e64 v77, 1.0, v65, s[44:45]
	v_xor_b32_e32 v65, 32, v219
	v_add_u32_e32 v67, 64, v67
	v_cmp_lt_i32_e32 vcc, v65, v67
	v_pk_mul_f32 v[116:117], v[74:75], v[72:73]
	v_mul_f32_e32 v64, v64, v120
	v_cndmask_b32_e32 v65, v219, v65, vcc
	v_lshlrev_b32_e32 v168, 2, v65
	v_mul_f32_e32 v65, v116, v117
	v_pk_mul_f32 v[116:117], v[78:79], v[76:77]
	v_mov_b32_e32 v72, v65
	s_nop 1
	v_permlane32_swap_b32_e32 v65, v72
	v_mul_f32_e32 v69, v116, v117
	v_mov_b32_e32 v76, v69
	s_nop 1
	v_permlane32_swap_b32_e32 v69, v76
	v_pk_mul_f32 v[116:117], v[114:115], v[70:71]
	v_cndmask_b32_e64 v64, 1.0, v64, s[12:13]
	v_pk_mul_f32 v[116:117], v[116:117], v[116:117] op_sel:[0,1] op_sel_hi:[1,0]
	v_mov_b32_e32 v67, v116
	s_nop 1
	v_permlane32_swap_b32_e32 v116, v67
	s_waitcnt lgkmcnt(0)
	v_mul_f32_e32 v113, v65, v72
	v_mul_f32_e32 v65, v69, v76
	v_mul_f32_e32 v69, v197, v65
	v_mov_b32_e32 v65, v116
	v_pk_mul_f32 v[64:65], v[64:65], v[66:67]
	v_pk_mul_f32 v[116:117], v[112:113], v[68:69]
	v_cndmask_b32_e64 v113, 1.0, v67, s[10:11]
	v_pk_mul_f32 v[118:119], v[64:65], v[116:117]
	v_mov_b32_e32 v116, v118
	s_nop 1
	v_permlane32_swap_b32_e32 v118, v116
	v_cndmask_b32_e64 v67, 1.0, v72, s[10:11]
	v_cndmask_b32_e64 v65, 0, v121, s[14:15]
	v_cndmask_b32_e64 v121, 0, v123, s[18:19]
	v_cndmask_b32_e64 v123, 0, v125, s[22:23]
	s_waitcnt lgkmcnt(0)
; DEV f32x16 mfma32(bf16x8 a, bf16x8 b, f32x16 c) { return __builtin_amdgcn_mfma_f32_32x32x16_bf16(a, b, c, 0, 0, 0); }
; template <bool DIAG>
; DEV void sb_tile(const char* lk, const char* lv, const int ko0, const int vo0, const bf16x8 (&qf)[8], f32x16 (&O)[4], float& accp,
;                  const int l31, const int hh) {
;     ...
;   for (int q = 0; q < 4; ++q) { gp[q] = (om[4 * q] * om[4 * q + 1]) * (om[4 * q + 2] * om[4 * q + 3]); pp[q] = __shfl_xor(gp[q], 32); tot[q] = gp[q] * pp[q]; }
;   float suf[4];
;   suf[3] = accp; suf[2] = suf[3] * tot[3]; suf[1] = suf[2] * tot[2]; suf[0] = suf[1] * tot[1];
;   accp = suf[0] * tot[0];
;   f32x16 w;
; #pragma unroll
;   for (int q = 0; q < 4; ++q) {
;     float a = suf[q] * (hh == 0 ? pp[q] : 1.f);
;     w[4 * q + 3] = be[4 * q + 3] * a; a *= om[4 * q + 3];
;     w[4 * q + 2] = be[4 * q + 2] * a; a *= om[4 * q + 2];
;     w[4 * q + 1] = be[4 * q + 1] * a; a *= om[4 * q + 1];
;     w[4 * q + 0] = be[4 * q + 0] * a;
;   }
;   const bf16x8 w0 = cvt8<0>(w), w1 = cvt8<1>(w);
; #pragma unroll
;   for (int d = 0; d < 4; ++d) { O[d] = mfma32(vf[d][0], w0, O[d]); O[d] = mfma32(vf[d][1], w1, O[d]); }
	v_cndmask_b32_e64 v70, 1.0, v116, s[10:11]
	v_cndmask_b32_e64 v125, 0, v127, s[26:27]
	v_cndmask_b32_e64 v127, 0, v161, s[30:31]
	v_cndmask_b32_e64 v161, 0, v163, s[36:37]
	v_cndmask_b32_e64 v163, 0, v165, s[40:41]
	v_cndmask_b32_e64 v165, 0, v167, s[44:45]
	v_mul_f32_e32 v167, v67, v69
	v_mul_f32_e32 v69, v70, v119
	v_mul_f32_e32 v68, v68, v69
	v_mul_f32_e32 v67, v112, v68
	v_cndmask_b32_e64 v64, 0, v120, s[12:13]
	v_cndmask_b32_e64 v120, 0, v122, s[16:17]
	v_mul_f32_e32 v66, v66, v67
	v_pk_mul_f32 v[64:65], v[64:65], v[66:67]
	v_pk_mul_f32 v[66:67], v[120:121], v[68:69]
	v_mul_f32_e32 v69, v113, v117
	v_mul_f32_e32 v68, v71, v69
	v_mul_f32_e32 v71, v115, v68
	v_cndmask_b32_e64 v122, 0, v124, s[20:21]
	v_cndmask_b32_e64 v124, 0, v126, s[24:25]
	v_mul_f32_e32 v70, v114, v71
	v_pk_mul_f32 v[70:71], v[122:123], v[70:71]
	v_pk_mul_f32 v[68:69], v[124:125], v[68:69]
	v_cvt_pk_bf16_f32 v64, v64, v65
	v_cvt_pk_bf16_f32 v65, v66, v67
	v_cvt_pk_bf16_f32 v66, v70, v71
	v_cvt_pk_bf16_f32 v67, v68, v69
	v_cndmask_b32_e64 v76, 1.0, v76, s[10:11]
	v_mul_f32_e32 v113, v197, v76
	v_mfma_f32_32x32x16_bf16 v[48:63], v[108:111], v[64:67], v[48:63]
	v_cndmask_b32_e64 v126, 0, v160, s[28:29]
	v_cndmask_b32_e64 v160, 0, v162, s[34:35]
	v_cndmask_b32_e64 v162, 0, v164, s[38:39]
	v_cndmask_b32_e64 v164, 0, v166, s[42:43]
	v_mul_f32_e32 v166, v73, v167
	v_mul_f32_e32 v112, v113, v77
	v_mul_f32_e32 v75, v75, v166
	v_mfma_f32_32x32x16_bf16 v[32:47], v[96:99], v[64:67], v[32:47]
	v_mul_f32_e32 v69, v79, v112
	v_mul_f32_e32 v74, v74, v75
	v_mul_f32_e32 v68, v78, v69
	v_mul_f32_e64 v72, v160, v166
	v_mul_f32_e64 v73, v161, v167
	v_pk_mul_f32 v[74:75], v[126:127], v[74:75]
	v_pk_mul_f32 v[76:77], v[164:165], v[112:113]
	v_pk_mul_f32 v[70:71], v[162:163], v[68:69]
	v_mfma_f32_32x32x16_bf16 v[16:31], v[88:91], v[64:67], v[16:31]
	v_cvt_pk_bf16_f32 v68, v74, v75
	v_cvt_pk_bf16_f32 v69, v72, v73
	v_cvt_pk_bf16_f32 v70, v70, v71
	v_cvt_pk_bf16_f32 v71, v76, v77
	v_mfma_f32_32x32x16_bf16 v[0:15], v[84:87], v[64:67], v[0:15]
	v_mul_f32_e32 v64, v118, v116
	v_mul_f32_e32 v199, v64, v119
	v_mfma_f32_32x32x16_bf16 v[48:63], v[104:107], v[68:71], v[48:63]
	v_mfma_f32_32x32x16_bf16 v[32:47], v[100:103], v[68:71], v[32:47]
	v_mfma_f32_32x32x16_bf16 v[16:31], v[92:95], v[68:71], v[16:31]
	v_mfma_f32_32x32x16_bf16 v[0:15], v[80:83], v[68:71], v[0:15]
	s_nop 10
	v_mov_b64_e32 v[110:111], v[30:31]
	v_mov_b64_e32 v[94:95], v[46:47]
	v_mov_b64_e32 v[78:79], v[62:63]
	v_mov_b64_e32 v[108:109], v[28:29]
	v_mov_b64_e32 v[106:107], v[26:27]
	v_mov_b64_e32 v[104:105], v[24:25]
	v_mov_b64_e32 v[102:103], v[22:23]
	v_mov_b64_e32 v[126:127], v[14:15]
	v_mov_b64_e32 v[124:125], v[12:13]
	v_mov_b64_e32 v[122:123], v[10:11]
	v_mov_b64_e32 v[120:121], v[8:9]
	v_mov_b64_e32 v[118:119], v[6:7]
	v_mov_b64_e32 v[116:117], v[4:5]
	v_mov_b64_e32 v[114:115], v[2:3]
	v_mov_b64_e32 v[112:113], v[0:1]
	v_mov_b64_e32 v[100:101], v[20:21]
	v_mov_b64_e32 v[98:99], v[18:19]
	v_mov_b64_e32 v[96:97], v[16:17]
	v_mov_b64_e32 v[92:93], v[44:45]
	v_mov_b64_e32 v[90:91], v[42:43]
	v_mov_b64_e32 v[88:89], v[40:41]
	v_mov_b64_e32 v[86:87], v[38:39]
	v_mov_b64_e32 v[84:85], v[36:37]
	v_mov_b64_e32 v[82:83], v[34:35]
	v_mov_b64_e32 v[80:81], v[32:33]
	v_mov_b64_e32 v[76:77], v[60:61]
	v_mov_b64_e32 v[74:75], v[58:59]
	v_mov_b64_e32 v[72:73], v[56:57]
	v_mov_b64_e32 v[70:71], v[54:55]
	v_mov_b64_e32 v[68:69], v[52:53]
	v_mov_b64_e32 v[66:67], v[50:51]
	v_mov_b64_e32 v[64:65], v[48:49]
; DEV f32x16 mfma32(bf16x8 a, bf16x8 b, f32x16 c) { return __builtin_amdgcn_mfma_f32_32x32x16_bf16(a, b, c, 0, 0, 0); }
; template <bool DIAG>
; DEV void sb_tile(const char* lk, const char* lv, const int ko0, const int vo0, const bf16x8 (&qf)[8], f32x16 (&O)[4], float& accp,
;                  const int l31, const int hh) {
;   f32x16 z;
;   for (int g = 0; g < 16; ++g) z[g] = 0.f;
;   {
;     bf16x8 kf[8];
; #pragma unroll
;     for (int s = 0; s < 8; ++s) kf[s] = *(const bf16x8*)(lk + (ko0 ^ (32 * s)));
;     __builtin_amdgcn_sched_barrier(0);
; #pragma unroll
;     for (int s = 0; s < 8; ++s) z = mfma32(kf[s], qf[s], z);
;   }
;   bf16x8 vf[4][2];
; #pragma unroll
;   for (int d = 0; d < 4; ++d) { vf[d][0] = *(const bf16x8*)(lv + d * 4096 + vo0); vf[d][1] = *(const bf16x8*)(lv + d * 4096 + (vo0 ^ 32)); }
;   __builtin_amdgcn_sched_barrier(0);
;   float be[16], om[16];
; #pragma unroll
;   for (int g = 0; g < 16; ++g) {
;     const float e = __builtin_amdgcn_exp2f(fminf(-z[g], 120.f));
;     be[g] = __builtin_amdgcn_rcpf(1.f + e);
;     om[g] = e * be[g];
;     if (DIAG) { const int kl = (g & 3) + 8 * (g >> 2) + 4 * hh; if (kl >= l31) { be[g] = 0.f; om[g] = 1.f; } }
;   }
;   float gp[4], pp[4], tot[4];
; #pragma unroll
;   for (int q = 0; q < 4; ++q) { gp[q] = (om[4 * q] * om[4 * q + 1]) * (om[4 * q + 2] * om[4 * q + 3]); pp[q] = __shfl_xor(gp[q], 32); tot[q] = gp[q] * pp[q]; }
;   float suf[4];
;   suf[3] = accp; suf[2] = suf[3] * tot[3]; suf[1] = suf[2] * tot[2]; suf[0] = suf[1] * tot[1];
;   accp = suf[0] * tot[0];
;   f32x16 w;
; #pragma unroll
;   for (int q = 0; q < 4; ++q) {
;     float a = suf[q] * (hh == 0 ? pp[q] : 1.f);
; DEV void sb_block(const Params& p, int item) {
;     ...
;     else if (2 * j + 1 < qt) sb_tile<false>(lb_ + 32 * 256, lb_, ko0, vo0 ^ 64, qf, O, accp, l31, hh);
;     if (2 * j == qt) sb_tile<true>(lb_, lb_, ko0, vo0, qf, O, accp, l31, hh);
;     else if (2 * j < qt) sb_tile<false>(lb_, lb_, ko0, vo0, qf, O, accp, l31, hh);
.LBB0_565:
	s_cmp_lg_u32 s88, s69
	s_mov_b64 s[66:67], -1
	s_cbranch_scc0 .LBB0_569
	s_add_i32 s0, s0, 6
	s_cmp_ge_i32 s0, s75
	s_cbranch_scc1 .Lsb_skip_B0
	ds_read_b128 v[0:3], v240
	ds_read_b128 v[16:19], v241
	ds_read_b128 v[20:23], v242
	ds_read_b128 v[24:27], v243
	ds_read_b128 v[28:31], v244
	ds_read_b128 v[32:35], v245
	ds_read_b128 v[36:39], v246
	ds_read_b128 v[40:43], v247
	s_waitcnt lgkmcnt(0)
	v_mfma_f32_32x32x16_bf16 v[0:15], v[0:3], v[128:131], 0
	v_mfma_f32_32x32x16_bf16 v[0:15], v[16:19], v[132:135], v[0:15]
	v_mfma_f32_32x32x16_bf16 v[0:15], v[20:23], v[136:139], v[0:15]
	v_mfma_f32_32x32x16_bf16 v[0:15], v[24:27], v[140:143], v[0:15]
	v_mfma_f32_32x32x16_bf16 v[0:15], v[28:31], v[144:147], v[0:15]
	v_mfma_f32_32x32x16_bf16 v[0:15], v[32:35], v[148:151], v[0:15]
	ds_read_b128 v[28:31], v248
	ds_read_b128 v[16:19], v248 offset:4096
	ds_read_b128 v[24:27], v249
	ds_read_b128 v[20:23], v249 offset:4096
	ds_read_b128 v[168:171], v248 offset:8192
	ds_read_b128 v[164:167], v248 offset:12288
	ds_read_b128 v[172:175], v249 offset:8192
	ds_read_b128 v[160:163], v249 offset:12288
	v_mfma_f32_32x32x16_bf16 v[0:15], v[36:39], v[152:155], v[0:15]
	v_mfma_f32_32x32x16_bf16 v[0:15], v[40:43], v[156:159], v[0:15]
	s_nop 11
	v_min_f32_e64 v4, -v4, s32
	v_exp_f32_e32 v34, v4
	v_min_f32_e64 v4, -v5, s32
	v_exp_f32_e32 v35, v4
	v_add_f32_e32 v4, 1.0, v34
	v_min_f32_e64 v9, -v9, s32
	v_add_f32_e32 v5, 1.0, v35
	v_rcp_f32_e32 v4, v4
	v_rcp_f32_e32 v5, v5
	v_exp_f32_e32 v40, v9
	v_max_f32_e64 v9, -v10, -v10
	v_max_f32_e64 v10, -v11, -v11
	v_min_f32_e64 v8, -v8, s32
	v_min_f32_e32 v10, 0x42f00000, v10
	v_min_f32_e64 v11, -v13, s32
	v_max_f32_e64 v13, -v15, -v15
	v_and_b32_e32 v15, 64, v219
	v_exp_f32_e32 v8, v8
	v_exp_f32_e32 v41, v10
	v_max_f32_e64 v10, -v12, -v12
	v_exp_f32_e32 v12, v11
	v_max_f32_e64 v11, -v14, -v14
	v_xor_b32_e32 v14, 32, v219
	v_add_u32_e32 v15, 64, v15
	v_min_f32_e32 v9, 0x42f00000, v9
	v_cmp_lt_i32_e32 vcc, v14, v15
	v_pk_mul_f32 v[34:35], v[34:35], v[4:5]
	v_exp_f32_e32 v9, v9
	v_cndmask_b32_e32 v14, v219, v14, vcc
	v_lshlrev_b32_e32 v57, 2, v14
	v_pk_mul_f32 v[14:15], v[34:35], v[34:35] op_sel_hi:[0,1]
	v_add_f32_e32 v14, 1.0, v8
	v_rcp_f32_e32 v44, v14
	v_add_f32_e32 v14, 1.0, v40
	v_rcp_f32_e32 v46, v14
	v_add_f32_e32 v14, 1.0, v9
	v_rcp_f32_e32 v45, v14
	v_add_f32_e32 v14, 1.0, v41
	v_min_f32_e32 v10, 0x42f00000, v10
	v_rcp_f32_e32 v47, v14
	v_exp_f32_e32 v10, v10
	v_min_f32_e32 v11, 0x42f00000, v11
	v_exp_f32_e32 v11, v11
	v_min_f32_e32 v13, 0x42f00000, v13
	v_exp_f32_e32 v13, v13
	v_pk_mul_f32 v[8:9], v[8:9], v[44:45]
	v_pk_mul_f32 v[40:41], v[40:41], v[46:47]
	v_pk_mul_f32 v[48:49], v[8:9], v[40:41]
	v_add_f32_e32 v8, 1.0, v10
	v_rcp_f32_e32 v50, v8
	v_add_f32_e32 v8, 1.0, v12
	v_rcp_f32_e32 v52, v8
	v_add_f32_e32 v8, 1.0, v11
	v_min_f32_e64 v6, -v6, s32
	v_rcp_f32_e32 v51, v8
	v_add_f32_e32 v8, 1.0, v13
	v_exp_f32_e32 v36, v6
	v_rcp_f32_e32 v53, v8
	v_min_f32_e64 v6, -v7, s32
	v_min_f32_e64 v3, -v3, s32
	v_exp_f32_e32 v37, v6
	v_min_f32_e64 v0, -v0, s32
	v_exp_f32_e32 v198, v3
	v_exp_f32_e32 v32, v0
	v_pk_mul_f32 v[10:11], v[10:11], v[50:51]
	v_pk_mul_f32 v[12:13], v[12:13], v[52:53]
	v_add_f32_e32 v6, 1.0, v36
	v_pk_mul_f32 v[54:55], v[10:11], v[12:13]
	v_add_f32_e32 v7, 1.0, v37
	v_mul_f32_e32 v8, v54, v55
	v_add_f32_e32 v3, 1.0, v198
	v_rcp_f32_e32 v6, v6
	v_rcp_f32_e32 v7, v7
	v_pk_mul_f32 v[48:49], v[48:49], v[48:49] op_sel:[0,1] op_sel_hi:[1,0]
	v_mov_b32_e32 v10, v8
	s_nop 1
	v_permlane32_swap_b32_e32 v8, v10
	v_add_f32_e32 v0, 1.0, v32
	v_min_f32_e64 v2, -v2, s32
	v_rcp_f32_e32 v3, v3
	v_mov_b32_e32 v49, v48
	s_nop 1
	v_permlane32_swap_b32_e32 v48, v49
	v_rcp_f32_e32 v0, v0
	v_min_f32_e64 v1, -v1, s32
	v_exp_f32_e32 v38, v2
	v_exp_f32_e32 v56, v1
	v_pk_mul_f32 v[36:37], v[36:37], v[6:7]
	s_waitcnt lgkmcnt(0)
	v_mul_f32_e32 v55, v8, v10
	v_pk_mul_f32 v[42:43], v[36:37], v[36:37] op_sel_hi:[0,1]
	v_mov_b32_e32 v54, v3
	v_add_f32_e32 v2, 1.0, v38
	v_mov_b32_e32 v33, v15
	v_cndmask_b32_e64 v8, 1.0, v49, s[10:11]
	v_mov_b32_e32 v14, v45
	v_mov_b32_e32 v15, v47
	v_mov_b32_e32 v45, v46
	v_pk_mul_f32 v[46:47], v[198:199], v[54:55]
	v_mov_b32_e32 v42, v0
	v_add_f32_e32 v1, 1.0, v56
	v_rcp_f32_e32 v2, v2
	v_mul_f32_e32 v55, v8, v47
	v_pk_mul_f32 v[32:33], v[32:33], v[42:43]
	v_rcp_f32_e32 v1, v1
	v_mul_f32_e32 v54, v41, v55
	v_mov_b32_e32 v41, v33
	s_nop 1
	v_permlane32_swap_b32_e32 v33, v41
	v_mov_b32_e32 v39, v48
	v_mov_b32_e32 v48, v2
	v_mul_f32_e32 v9, v9, v54
	v_pk_mul_f32 v[38:39], v[38:39], v[48:49]
	v_mul_f32_e32 v8, v40, v9
	v_mul_f32_e32 v40, v56, v1
	v_pk_mul_f32 v[48:49], v[38:39], v[46:47]
	s_waitcnt lgkmcnt(0)
	v_pk_mul_f32 v[32:33], v[32:33], v[40:41]
	v_cndmask_b32_e64 v34, 1.0, v41, s[10:11]
	v_pk_mul_f32 v[32:33], v[32:33], v[48:49]
	v_mov_b32_e32 v39, v32
	s_nop 1
	v_permlane32_swap_b32_e32 v32, v39
	v_cndmask_b32_e64 v10, 1.0, v10, s[10:11]
	v_pk_mul_f32 v[14:15], v[14:15], v[54:55]
	v_pk_mul_f32 v[8:9], v[44:45], v[8:9]
	v_cvt_pk_bf16_f32 v225, v14, v15
	s_waitcnt lgkmcnt(0)
	v_mul_f32_e32 v32, v32, v39
	v_mul_f32_e32 v197, v32, v33
	v_cndmask_b32_e64 v32, 1.0, v39, s[10:11]
	v_mul_f32_e32 v33, v32, v33
	v_mul_f32_e32 v32, v46, v33
	v_pk_mul_f32 v[2:3], v[2:3], v[32:33]
	v_mul_f32_e32 v33, v34, v49
	v_mul_f32_e32 v39, v38, v32
	v_mul_f32_e32 v32, v37, v33
	v_mul_f32_e32 v37, v36, v32
	v_mul_f32_e32 v36, v35, v37
	v_mul_f32_e32 v35, v199, v10
	v_mul_f32_e32 v38, v40, v39
	v_mul_f32_e32 v34, v13, v35
	v_pk_mul_f32 v[0:1], v[0:1], v[38:39]
	v_pk_mul_f32 v[4:5], v[4:5], v[36:37]
	v_pk_mul_f32 v[6:7], v[6:7], v[32:33]
	v_mov_b32_e32 v32, v51
	v_mov_b32_e32 v33, v53
	v_mul_f32_e32 v11, v11, v34
	v_pk_mul_f32 v[32:33], v[32:33], v[34:35]
	v_mov_b32_e32 v51, v52
	v_mul_f32_e32 v10, v12, v11
	v_cvt_pk_bf16_f32 v214, v0, v1
	v_cvt_pk_bf16_f32 v215, v2, v3
	v_cvt_pk_bf16_f32 v216, v4, v5
	v_cvt_pk_bf16_f32 v217, v6, v7
	v_pk_mul_f32 v[10:11], v[50:51], v[10:11]
	v_cvt_pk_bf16_f32 v227, v32, v33
	v_mfma_f32_32x32x16_bf16 v[48:63], v[28:31], v[214:217], v[64:79]
	v_cvt_pk_bf16_f32 v224, v8, v9
	v_cvt_pk_bf16_f32 v226, v10, v11
	v_mfma_f32_32x32x16_bf16 v[32:47], v[16:19], v[214:217], v[80:95]
	s_nop 0
	v_mfma_f32_32x32x16_bf16 v[48:63], v[24:27], v[224:227], v[48:63]
	v_mfma_f32_32x32x16_bf16 v[32:47], v[20:23], v[224:227], v[32:47]
	v_mfma_f32_32x32x16_bf16 v[16:31], v[168:171], v[214:217], v[96:111]
	v_mfma_f32_32x32x16_bf16 v[0:15], v[164:167], v[214:217], v[112:127]
	v_mfma_f32_32x32x16_bf16 v[16:31], v[172:175], v[224:227], v[16:31]
	v_mfma_f32_32x32x16_bf16 v[0:15], v[160:163], v[224:227], v[0:15]

; DEV f32x16 mfma32(bf16x8 a, bf16x8 b, f32x16 c) { return __builtin_amdgcn_mfma_f32_32x32x16_bf16(a, b, c, 0, 0, 0); }
; template <bool DIAG>
; DEV void sb_tile(const char* lk, const char* lv, const int ko0, const int vo0, const bf16x8 (&qf)[8], f32x16 (&O)[4], float& accp,
;                  const int l31, const int hh) {
;   f32x16 z;
;   for (int g = 0; g < 16; ++g) z[g] = 0.f;
;   {
;     bf16x8 kf[8];
; #pragma unroll
;     for (int s = 0; s < 8; ++s) kf[s] = *(const bf16x8*)(lk + (ko0 ^ (32 * s)));
;     __builtin_amdgcn_sched_barrier(0);
; #pragma unroll
;     for (int s = 0; s < 8; ++s) z = mfma32(kf[s], qf[s], z);
;   }
;   bf16x8 vf[4][2];
; #pragma unroll
;   for (int d = 0; d < 4; ++d) { vf[d][0] = *(const bf16x8*)(lv + d * 4096 + vo0); vf[d][1] = *(const bf16x8*)(lv + d * 4096 + (vo0 ^ 32)); }
;   __builtin_amdgcn_sched_barrier(0);
;   float be[16], om[16];
; #pragma unroll
;   for (int g = 0; g < 16; ++g) {
;     const float e = __builtin_amdgcn_exp2f(fminf(-z[g], 120.f));
;     be[g] = __builtin_amdgcn_rcpf(1.f + e);
;     om[g] = e * be[g];
;     if (DIAG) { const int kl = (g & 3) + 8 * (g >> 2) + 4 * hh; if (kl >= l31) { be[g] = 0.f; om[g] = 1.f; } }
;   }
;   float gp[4], pp[4], tot[4];
; #pragma unroll
;   for (int q = 0; q < 4; ++q) { gp[q] = (om[4 * q] * om[4 * q + 1]) * (om[4 * q + 2] * om[4 * q + 3]); pp[q] = __shfl_xor(gp[q], 32); tot[q] = gp[q] * pp[q]; }
;   float suf[4];
;   suf[3] = accp; suf[2] = suf[3] * tot[3]; suf[1] = suf[2] * tot[2]; suf[0] = suf[1] * tot[1];
;   accp = suf[0] * tot[0];
;   f32x16 w;
; #pragma unroll
;   for (int q = 0; q < 4; ++q) {
;     float a = suf[q] * (hh == 0 ? pp[q] : 1.f);
; DEV void sb_block(const Params& p, int item) {
;     ...
;     if (2 * j + 1 == qt) sb_tile<true>(lb_ + 32 * 256, lb_, ko0, vo0 ^ 64, qf, O, accp, l31, hh);
;     else if (2 * j + 1 < qt) sb_tile<false>(lb_ + 32 * 256, lb_, ko0, vo0 ^ 64, qf, O, accp, l31, hh);
;     if (2 * j == qt) sb_tile<true>(lb_, lb_, ko0, vo0, qf, O, accp, l31, hh);
.LBB0_570:
	s_nop 9
	ds_read_b128 v[0:3], v240
	ds_read_b128 v[16:19], v241
	ds_read_b128 v[20:23], v242
	ds_read_b128 v[24:27], v243
	ds_read_b128 v[28:31], v244
	ds_read_b128 v[32:35], v245
	ds_read_b128 v[36:39], v246
	ds_read_b128 v[48:51], v247
	s_waitcnt lgkmcnt(0)
	v_mfma_f32_32x32x16_bf16 v[0:15], v[0:3], v[128:131], 0
	v_mfma_f32_32x32x16_bf16 v[0:15], v[16:19], v[132:135], v[0:15]
	v_mfma_f32_32x32x16_bf16 v[0:15], v[20:23], v[136:139], v[0:15]
	v_mfma_f32_32x32x16_bf16 v[0:15], v[24:27], v[140:143], v[0:15]
	v_mfma_f32_32x32x16_bf16 v[0:15], v[28:31], v[144:147], v[0:15]
	v_mfma_f32_32x32x16_bf16 v[0:15], v[32:35], v[148:151], v[0:15]
	v_mfma_f32_32x32x16_bf16 v[0:15], v[36:39], v[152:155], v[0:15]
	ds_read_b128 v[44:47], v248
	ds_read_b128 v[32:35], v248 offset:4096
	ds_read_b128 v[40:43], v249
	ds_read_b128 v[36:39], v249 offset:4096
	ds_read_b128 v[24:27], v248 offset:8192
	ds_read_b128 v[20:23], v248 offset:12288
	ds_read_b128 v[28:31], v249 offset:8192
	ds_read_b128 v[16:19], v249 offset:12288
	v_mfma_f32_32x32x16_bf16 v[0:15], v[48:51], v[156:159], v[0:15]
	s_nop 11
	v_min_f32_e64 v0, -v0, s32
	v_exp_f32_e32 v0, v0
	v_min_f32_e64 v1, -v1, s32
	v_exp_f32_e32 v1, v1
	v_add_f32_e32 v48, 1.0, v0
	v_rcp_f32_e32 v56, v48
	v_add_f32_e32 v48, 1.0, v1
	v_min_f32_e64 v2, -v2, s32
	v_rcp_f32_e32 v57, v48
	v_exp_f32_e32 v48, v2
	v_min_f32_e64 v2, -v3, s32
	v_exp_f32_e32 v3, v2
	v_add_f32_e32 v2, 1.0, v48
	v_rcp_f32_e32 v58, v2
	v_mul_f32_e32 v1, v1, v57
	v_add_f32_e32 v2, 1.0, v3
	v_rcp_f32_e32 v59, v2
	v_cndmask_b32_e64 v2, 1.0, v1, s[14:15]
	v_mul_f32_e32 v1, v48, v58
	v_cndmask_b32_e64 v48, 1.0, v1, s[16:17]
	v_mul_f32_e32 v1, v3, v59
	v_min_f32_e64 v3, -v4, s32
	v_exp_f32_e32 v3, v3
	v_min_f32_e64 v4, -v5, s32
	v_exp_f32_e32 v5, v4
	v_cndmask_b32_e64 v4, 1.0, v1, s[18:19]
	v_add_f32_e32 v1, 1.0, v3
	v_rcp_f32_e32 v60, v1
	v_add_f32_e32 v1, 1.0, v5
	v_rcp_f32_e32 v61, v1
	v_min_f32_e64 v1, -v6, s32
	v_exp_f32_e32 v1, v1
	v_mul_f32_e32 v3, v3, v60
	v_cndmask_b32_e64 v6, 1.0, v3, s[20:21]
	v_mul_f32_e32 v3, v5, v61
	v_add_f32_e32 v5, 1.0, v1
	v_rcp_f32_e32 v62, v5
	v_min_f32_e64 v5, -v7, s32
	v_exp_f32_e32 v5, v5
	v_mul_f32_e32 v1, v1, v62
	v_cndmask_b32_e64 v51, 1.0, v1, s[24:25]
	v_cndmask_b32_e64 v50, 1.0, v3, s[22:23]
	v_add_f32_e32 v1, 1.0, v5
	v_rcp_f32_e32 v63, v1
	v_min_f32_e64 v1, -v8, s32
	v_exp_f32_e32 v1, v1
	v_min_f32_e64 v3, -v9, s32
	v_exp_f32_e32 v3, v3
	v_mul_f32_e32 v5, v5, v63
	v_add_f32_e32 v7, 1.0, v1
	v_rcp_f32_e32 v160, v7
	v_add_f32_e32 v7, 1.0, v3
	v_rcp_f32_e32 v161, v7
	v_cndmask_b32_e64 v7, 1.0, v5, s[26:27]
	v_mul_f32_e32 v1, v1, v160
	v_cndmask_b32_e64 v8, 1.0, v1, s[28:29]
	v_mul_f32_e32 v1, v3, v161
	v_min_f32_e64 v3, -v10, s32
	v_exp_f32_e32 v3, v3
	v_min_f32_e64 v5, -v11, s32
	v_exp_f32_e32 v5, v5
	v_cndmask_b32_e64 v10, 1.0, v1, s[30:31]
	v_add_f32_e32 v1, 1.0, v3
	v_rcp_f32_e32 v162, v1
	v_add_f32_e32 v1, 1.0, v5
	v_rcp_f32_e32 v163, v1
	v_min_f32_e64 v1, -v12, s32
	v_exp_f32_e32 v1, v1
	v_mul_f32_e32 v3, v3, v162
	v_cndmask_b32_e64 v11, 1.0, v3, s[34:35]
	v_mul_f32_e32 v3, v5, v163
	v_add_f32_e32 v5, 1.0, v1
	v_rcp_f32_e32 v164, v5
	v_min_f32_e64 v5, -v13, s32
	v_exp_f32_e32 v5, v5
	v_mul_f32_e32 v1, v1, v164
	v_cndmask_b32_e64 v12, 1.0, v1, s[38:39]
	v_cndmask_b32_e64 v9, 1.0, v3, s[36:37]
	v_add_f32_e32 v1, 1.0, v5
	v_rcp_f32_e32 v165, v1
	v_min_f32_e64 v1, -v14, s32
	v_exp_f32_e32 v1, v1
	v_min_f32_e64 v3, -v15, s32
	v_exp_f32_e32 v3, v3
	v_mul_f32_e32 v5, v5, v165
	v_add_f32_e32 v13, 1.0, v1
	v_rcp_f32_e32 v166, v13
	v_add_f32_e32 v13, 1.0, v3
	v_rcp_f32_e32 v167, v13
	v_cndmask_b32_e64 v14, 1.0, v5, s[40:41]
	v_mul_f32_e32 v1, v1, v166
	v_cndmask_b32_e64 v15, 1.0, v1, s[42:43]
	v_mul_f32_e32 v1, v3, v167
	v_and_b32_e32 v3, 64, v219
	v_cndmask_b32_e64 v13, 1.0, v1, s[44:45]
	v_xor_b32_e32 v1, 32, v219
	v_add_u32_e32 v3, 64, v3
	v_cmp_lt_i32_e32 vcc, v1, v3
	v_pk_mul_f32 v[52:53], v[10:11], v[8:9]
	v_mul_f32_e32 v0, v0, v56
	v_cndmask_b32_e32 v1, v219, v1, vcc
	v_lshlrev_b32_e32 v168, 2, v1
	v_mul_f32_e32 v1, v52, v53
	v_pk_mul_f32 v[52:53], v[14:15], v[12:13]
	v_mov_b32_e32 v8, v1
	s_nop 1
	v_permlane32_swap_b32_e32 v1, v8
	v_mul_f32_e32 v5, v52, v53
	v_mov_b32_e32 v12, v5
	s_nop 1
	v_permlane32_swap_b32_e32 v5, v12
	v_pk_mul_f32 v[52:53], v[50:51], v[6:7]
	v_cndmask_b32_e64 v0, 1.0, v0, s[12:13]
	v_pk_mul_f32 v[52:53], v[52:53], v[52:53] op_sel:[0,1] op_sel_hi:[1,0]
	v_mov_b32_e32 v3, v52
	s_nop 1
	v_permlane32_swap_b32_e32 v52, v3
	s_waitcnt lgkmcnt(0)
; DEV f32x16 mfma32(bf16x8 a, bf16x8 b, f32x16 c) { return __builtin_amdgcn_mfma_f32_32x32x16_bf16(a, b, c, 0, 0, 0); }
; template <bool DIAG>
; DEV void sb_tile(const char* lk, const char* lv, const int ko0, const int vo0, const bf16x8 (&qf)[8], f32x16 (&O)[4], float& accp,
;                  const int l31, const int hh) {
;     ...
;   for (int q = 0; q < 4; ++q) { gp[q] = (om[4 * q] * om[4 * q + 1]) * (om[4 * q + 2] * om[4 * q + 3]); pp[q] = __shfl_xor(gp[q], 32); tot[q] = gp[q] * pp[q]; }
;   float suf[4];
;   suf[3] = accp; suf[2] = suf[3] * tot[3]; suf[1] = suf[2] * tot[2]; suf[0] = suf[1] * tot[1];
;   accp = suf[0] * tot[0];
;   f32x16 w;
; #pragma unroll
;   for (int q = 0; q < 4; ++q) {
;     float a = suf[q] * (hh == 0 ? pp[q] : 1.f);
;     w[4 * q + 3] = be[4 * q + 3] * a; a *= om[4 * q + 3];
;     w[4 * q + 2] = be[4 * q + 2] * a; a *= om[4 * q + 2];
;     w[4 * q + 1] = be[4 * q + 1] * a; a *= om[4 * q + 1];
;     w[4 * q + 0] = be[4 * q + 0] * a;
;   }
;   const bf16x8 w0 = cvt8<0>(w), w1 = cvt8<1>(w);
; #pragma unroll
;   for (int d = 0; d < 4; ++d) { O[d] = mfma32(vf[d][0], w0, O[d]); O[d] = mfma32(vf[d][1], w1, O[d]); }
	v_mul_f32_e32 v49, v1, v8
	v_mul_f32_e32 v1, v5, v12
	v_mul_f32_e32 v5, v199, v1
	v_mov_b32_e32 v1, v52
	v_pk_mul_f32 v[0:1], v[0:1], v[2:3]
	v_pk_mul_f32 v[52:53], v[48:49], v[4:5]
	v_cndmask_b32_e64 v49, 1.0, v3, s[10:11]
	v_pk_mul_f32 v[54:55], v[0:1], v[52:53]
	v_mov_b32_e32 v52, v54
	s_nop 1
	v_permlane32_swap_b32_e32 v54, v52
	v_cndmask_b32_e64 v3, 1.0, v8, s[10:11]
	v_cndmask_b32_e64 v1, 0, v57, s[14:15]
	v_cndmask_b32_e64 v57, 0, v59, s[18:19]
	v_cndmask_b32_e64 v59, 0, v61, s[22:23]
	s_waitcnt lgkmcnt(0)
	v_cndmask_b32_e64 v6, 1.0, v52, s[10:11]
	v_cndmask_b32_e64 v61, 0, v63, s[26:27]
	v_cndmask_b32_e64 v63, 0, v161, s[30:31]
	v_cndmask_b32_e64 v161, 0, v163, s[36:37]
	v_cndmask_b32_e64 v163, 0, v165, s[40:41]
	v_cndmask_b32_e64 v165, 0, v167, s[44:45]
	v_mul_f32_e32 v167, v3, v5
	v_mul_f32_e32 v5, v6, v55
	v_mul_f32_e32 v4, v4, v5
	v_mul_f32_e32 v3, v48, v4
	v_cndmask_b32_e64 v0, 0, v56, s[12:13]
	v_cndmask_b32_e64 v56, 0, v58, s[16:17]
	v_mul_f32_e32 v2, v2, v3
	v_pk_mul_f32 v[0:1], v[0:1], v[2:3]
	v_pk_mul_f32 v[2:3], v[56:57], v[4:5]
	v_mul_f32_e32 v5, v49, v53
	v_mul_f32_e32 v4, v7, v5
	v_mul_f32_e32 v7, v51, v4
	v_cndmask_b32_e64 v58, 0, v60, s[20:21]
	v_cndmask_b32_e64 v60, 0, v62, s[24:25]
	v_mul_f32_e32 v6, v50, v7
	v_pk_mul_f32 v[6:7], v[58:59], v[6:7]
	v_pk_mul_f32 v[4:5], v[60:61], v[4:5]
	v_cvt_pk_bf16_f32 v0, v0, v1
	v_cvt_pk_bf16_f32 v1, v2, v3
	v_cvt_pk_bf16_f32 v2, v6, v7
	v_cvt_pk_bf16_f32 v3, v4, v5
	v_cndmask_b32_e64 v12, 1.0, v12, s[10:11]
	v_mul_f32_e32 v49, v199, v12
	v_mfma_f32_32x32x16_bf16 v[64:79], v[44:47], v[0:3], v[64:79]
	v_cndmask_b32_e64 v62, 0, v160, s[28:29]
	v_cndmask_b32_e64 v160, 0, v162, s[34:35]
	v_cndmask_b32_e64 v162, 0, v164, s[38:39]
	v_cndmask_b32_e64 v164, 0, v166, s[42:43]
	v_mul_f32_e32 v166, v9, v167
	v_mul_f32_e32 v48, v49, v13
	v_mul_f32_e32 v11, v11, v166
	v_mfma_f32_32x32x16_bf16 v[80:95], v[32:35], v[0:3], v[80:95]
	v_mul_f32_e32 v5, v15, v48
	v_mul_f32_e32 v10, v10, v11
	v_mul_f32_e32 v4, v14, v5
	v_mul_f32_e64 v8, v160, v166
	v_mul_f32_e64 v9, v161, v167
	v_pk_mul_f32 v[10:11], v[62:63], v[10:11]
	v_pk_mul_f32 v[12:13], v[164:165], v[48:49]
	v_pk_mul_f32 v[6:7], v[162:163], v[4:5]
	v_mfma_f32_32x32x16_bf16 v[96:111], v[24:27], v[0:3], v[96:111]
	v_cvt_pk_bf16_f32 v4, v10, v11
	v_cvt_pk_bf16_f32 v5, v8, v9
	v_cvt_pk_bf16_f32 v6, v6, v7
	v_cvt_pk_bf16_f32 v7, v12, v13
	v_mfma_f32_32x32x16_bf16 v[112:127], v[20:23], v[0:3], v[112:127]
	v_mul_f32_e32 v0, v54, v52
	v_mul_f32_e32 v197, v0, v55
	v_mfma_f32_32x32x16_bf16 v[64:79], v[40:43], v[4:7], v[64:79]
	v_mfma_f32_32x32x16_bf16 v[80:95], v[36:39], v[4:7], v[80:95]
	s_nop 10
	v_mov_b64_e32 v[48:49], v[64:65]
	v_mov_b64_e32 v[50:51], v[66:67]
	v_mov_b64_e32 v[52:53], v[68:69]
	v_mov_b64_e32 v[54:55], v[70:71]
	v_mov_b64_e32 v[56:57], v[72:73]
	v_mov_b64_e32 v[58:59], v[74:75]
	v_mov_b64_e32 v[60:61], v[76:77]
	v_mfma_f32_32x32x16_bf16 v[96:111], v[28:31], v[4:7], v[96:111]
	v_mov_b64_e32 v[32:33], v[80:81]
	v_mov_b64_e32 v[34:35], v[82:83]
	v_mov_b64_e32 v[36:37], v[84:85]
	v_mov_b64_e32 v[38:39], v[86:87]
	v_mov_b64_e32 v[40:41], v[88:89]
	v_mov_b64_e32 v[42:43], v[90:91]
	v_mov_b64_e32 v[44:45], v[92:93]
	v_mfma_f32_32x32x16_bf16 v[112:127], v[16:19], v[4:7], v[112:127]
	s_nop 3
	v_mov_b64_e32 v[16:17], v[96:97]
	v_mov_b64_e32 v[18:19], v[98:99]
	v_mov_b64_e32 v[20:21], v[100:101]
	v_mov_b64_e32 v[22:23], v[102:103]
	v_mov_b64_e32 v[24:25], v[104:105]
	v_mov_b64_e32 v[26:27], v[106:107]
	v_mov_b64_e32 v[28:29], v[108:109]
	s_nop 0
	v_mov_b64_e32 v[0:1], v[112:113]
	v_mov_b64_e32 v[2:3], v[114:115]
	v_mov_b64_e32 v[4:5], v[116:117]
	v_mov_b64_e32 v[6:7], v[118:119]
	v_mov_b64_e32 v[8:9], v[120:121]
	v_mov_b64_e32 v[10:11], v[122:123]
	v_mov_b64_e32 v[12:13], v[124:125]
	v_mov_b64_e32 v[14:15], v[126:127]
	v_mov_b64_e32 v[30:31], v[110:111]
	v_mov_b64_e32 v[46:47], v[94:95]
	v_mov_b64_e32 v[62:63], v[78:79]
	s_branch .LBB0_542

; DEV f32x16 mfma32(bf16x8 a, bf16x8 b, f32x16 c) { return __builtin_amdgcn_mfma_f32_32x32x16_bf16(a, b, c, 0, 0, 0); }
; template <bool DIAG>
; DEV void sb_tile(const char* lk, const char* lv, const int ko0, const int vo0, const bf16x8 (&qf)[8], f32x16 (&O)[4], float& accp,
;                  const int l31, const int hh) {
;     ...
;     for (int s = 0; s < 8; ++s) kf[s] = *(const bf16x8*)(lk + (ko0 ^ (32 * s)));
;     __builtin_amdgcn_sched_barrier(0);
; #pragma unroll
;     for (int s = 0; s < 8; ++s) z = mfma32(kf[s], qf[s], z);
;   }
;   bf16x8 vf[4][2];
; #pragma unroll
;   for (int d = 0; d < 4; ++d) { vf[d][0] = *(const bf16x8*)(lv + d * 4096 + vo0); vf[d][1] = *(const bf16x8*)(lv + d * 4096 + (vo0 ^ 32)); }
;   __builtin_amdgcn_sched_barrier(0);
;   float be[16], om[16];
; #pragma unroll
;   for (int g = 0; g < 16; ++g) {
;     const float e = __builtin_amdgcn_exp2f(fminf(-z[g], 120.f));
;     be[g] = __builtin_amdgcn_rcpf(1.f + e);
;     om[g] = e * be[g];
;     if (DIAG) { const int kl = (g & 3) + 8 * (g >> 2) + 4 * hh; if (kl >= l31) { be[g] = 0.f; om[g] = 1.f; } }
; DEV void sb_block(const Params& p, int item) {
;     ...
;   const bf16_t* vsrc = svT + ((size_t)(b * 2048 + h * 128 + (lane >> 3))) * 2048;
;     ...
;   const int KO0 = l31 * 256 + ((hh ^ (l31 & 15)) * 16);
;   const int VO0 = 16384 + l31 * 128 + ((hh ^ ((l31 >> 1) & 7)) * 16);
;   const int nsteps = 4 * qb + 4;
;   asm volatile("s_waitcnt vmcnt(0)" ::: "memory");
;   __syncthreads();
;   { const int j0 = nsteps - 1; SB_DMA(j0, 0); SB_DMA((j0 > 0 ? j0 - 1 : 0), 1); SB_DMA((j0 > 1 ? j0 - 2 : 0), 2); }
.LBB0_1193:
	v_lshlrev_b32_e32 v3, 8, v203
	v_xor_b32_e32 v5, v202, v14
	v_lshl_or_b32 v205, v5, 4, v3
	v_lshrrev_b32_e32 v5, 1, v201
	v_bitop3_b32 v5, v202, v5, 7 bitop3:0x78
	s_lshl_b32 s11, s11, 10
	v_lshlrev_b32_e32 v3, 7, v203
	v_lshlrev_b32_e32 v5, 4, v5
	s_movk_i32 s12, 0x4000
	s_add_i32 s11, s11, s10
	v_or3_b32 v206, v5, v3, s12
	v_add_u32_e32 v3, s11, v12
	v_mov_b32_e32 v5, v177
	v_readfirstlane_b32 s10, v3
	v_lshl_add_u64 v[4:5], v[4:5], 1, v[8:9]
	s_mov_b32 m0, s10
	v_lshlrev_b32_e32 v3, 2, v202
	global_load_lds_dwordx4 v[4:5], off
	v_or_b32_e32 v4, 1, v3
	v_cmp_lt_u32_e64 s[14:15], v4, v203
	v_or_b32_e32 v4, 2, v3
	v_cmp_lt_u32_e64 s[16:17], v4, v203
	v_or_b32_e32 v4, 3, v3
	v_cmp_lt_u32_e64 s[18:19], v4, v203
	v_or_b32_e32 v4, 8, v3
	v_cmp_lt_u32_e64 s[20:21], v4, v203
	v_or_b32_e32 v4, 9, v3
	v_cmp_lt_u32_e64 s[22:23], v4, v203
	v_or_b32_e32 v4, 10, v3
	v_cmp_lt_u32_e64 s[24:25], v4, v203
	v_or_b32_e32 v4, 11, v3
	v_cmp_lt_u32_e64 s[26:27], v4, v203
	v_or_b32_e32 v4, 16, v3
	v_cmp_lt_u32_e64 s[28:29], v4, v203
	v_or_b32_e32 v4, 17, v3
	v_cmp_lt_u32_e64 s[30:31], v4, v203
	v_or_b32_e32 v4, 18, v3
	v_cmp_lt_u32_e64 s[34:35], v4, v203
	v_or_b32_e32 v4, 19, v3
	v_cmp_lt_u32_e64 s[36:37], v4, v203
	v_or_b32_e32 v4, 24, v3
	s_add_i32 s65, s33, -16
	v_cmp_lt_u32_e64 s[38:39], v4, v203
	v_or_b32_e32 v4, 25, v3
	s_lshl_b32 s92, s65, 3
	v_cmp_lt_u32_e64 s[12:13], v3, v203
	v_cmp_lt_u32_e64 s[40:41], v4, v203
	v_or_b32_e32 v4, 26, v3
	v_or_b32_e32 v3, 27, v3
	s_lshl_b64 s[84:85], s[92:93], 12
	v_cmp_lt_u32_e64 s[44:45], v3, v203
	v_or_b32_e32 v3, s92, v10
	v_writelane_b32 v252, s84, 7
	v_lshrrev_b32_e32 v3, 1, v3
	s_lshl_b32 s3, s65, 10
	v_writelane_b32 v252, s85, 8
	s_lshl_b32 s65, s89, 4
	v_xor_b32_e32 v3, v3, v201
	v_writelane_b32 v252, s65, 9
	s_lshl_b32 s65, s89, 12
	v_lshlrev_b32_e32 v3, 3, v3
	v_writelane_b32 v252, s65, 10
	s_add_i32 s65, s33, -15
	v_and_b32_e32 v16, 56, v3
	v_mov_b32_e32 v3, v177
	s_lshl_b32 s92, s65, 3
	v_lshl_add_u64 v[184:185], v[0:1], 0, v[2:3]
	v_or_b32_e32 v2, s92, v10
	v_lshrrev_b32_e32 v2, 1, v2
	v_xor_b32_e32 v2, v2, v201
	s_add_i32 s33, s33, -14
	s_lshl_b64 s[84:85], s[92:93], 12
	v_lshlrev_b32_e32 v2, 3, v2
	s_lshl_b32 s92, s33, 3
	v_and_b32_e32 v18, 56, v2
	v_or_b32_e32 v2, s92, v10
	v_lshrrev_b32_e32 v2, 1, v2
	v_xor_b32_e32 v2, v2, v201
	v_lshlrev_b32_e32 v176, 4, v13
	v_lshlrev_b32_e32 v2, 3, v2
	v_lshl_add_u64 v[186:187], v[0:1], 0, v[176:177]
	v_and_b32_e32 v20, 56, v2
	v_lshlrev_b32_e32 v176, 4, v15
	v_mov_b32_e32 v7, v177
	v_mov_b32_e32 v14, v177
	v_mov_b32_e32 v15, v177
	v_cmp_gt_u32_e64 s[10:11], 32, v11
	v_cmp_lt_u32_e64 s[42:43], v4, v203
	v_writelane_b32 v252, s84, 11
	v_lshl_add_u64 v[188:189], v[0:1], 0, v[176:177]
	v_lshl_add_u64 v[190:191], v[6:7], 1, v[0:1]
	v_mov_b32_e32 v0, v177
	v_mov_b32_e32 v1, v177
	v_mov_b32_e32 v2, v177
	v_mov_b32_e32 v4, v177
	v_mov_b32_e32 v5, v177
	v_mov_b32_e32 v6, v177
	v_mov_b32_e32 v8, v177
	v_mov_b32_e32 v9, v177
	v_mov_b32_e32 v10, v177
	v_mov_b32_e32 v11, v177
	v_mov_b32_e32 v12, v177
	v_mov_b32_e32 v13, v177
	v_lshlrev_b32_e32 v176, 1, v16
	v_lshlrev_b32_e32 v192, 1, v18
	v_lshlrev_b32_e32 v194, 1, v20
	v_mov_b64_e32 v[30:31], v[14:15]
	v_mov_b64_e32 v[46:47], v[14:15]
	v_mov_b64_e32 v[62:63], v[14:15]
	v_writelane_b32 v252, s85, 12
	s_lshl_b32 s79, s65, 10
	s_lshl_b32 s75, s64, 2
	s_lshl_b32 s84, s64, 10
	s_lshl_b64 s[64:65], s[92:93], 12
	s_lshl_b32 s85, s33, 10
	s_lshl_b32 s68, s66, 2
	s_lshl_b32 s70, s66, 10
	v_mov_b32_e32 v183, v177
	s_lshl_b32 s86, s69, 10
	s_lshl_b32 s87, s67, 10
	s_add_i32 s88, s89, -6
	s_mov_b32 s91, s89
	s_add_i32 s89, s89, -7
	s_add_i32 s71, s71, 3
	v_mov_b32_e32 v197, 1.0
	s_mov_b32 s33, 0
	s_mov_b32 s69, 0
	v_mov_b64_e32 v[28:29], v[12:13]
	v_mov_b64_e32 v[26:27], v[10:11]
	v_mov_b64_e32 v[24:25], v[8:9]
	v_mov_b64_e32 v[22:23], v[6:7]
	v_mov_b64_e32 v[20:21], v[4:5]
	v_mov_b64_e32 v[18:19], v[2:3]
	v_mov_b64_e32 v[16:17], v[0:1]
	v_mov_b64_e32 v[44:45], v[12:13]
	v_mov_b64_e32 v[42:43], v[10:11]
	v_mov_b64_e32 v[40:41], v[8:9]
	v_mov_b64_e32 v[38:39], v[6:7]
	v_mov_b64_e32 v[36:37], v[4:5]
	v_mov_b64_e32 v[34:35], v[2:3]
	v_mov_b64_e32 v[32:33], v[0:1]
	v_mov_b64_e32 v[60:61], v[12:13]
	v_mov_b64_e32 v[58:59], v[10:11]
	v_mov_b64_e32 v[56:57], v[8:9]
	v_mov_b64_e32 v[54:55], v[6:7]
	v_mov_b64_e32 v[52:53], v[4:5]
	v_mov_b64_e32 v[50:51], v[2:3]
	v_mov_b64_e32 v[48:49], v[0:1]
	s_waitcnt vmcnt(0)
	v_mov_b32_e32 v228, v205
	v_xor_b32_e32 v229, 32, v205
	v_xor_b32_e32 v230, 64, v205
	v_xor_b32_e32 v231, 0x60, v205
	v_xor_b32_e32 v232, 0x80, v205
	v_xor_b32_e32 v233, 0xa0, v205
	v_xor_b32_e32 v234, 0xc0, v205
	v_xor_b32_e32 v235, 0xe0, v205
	v_mov_b32_e32 v236, v206
	v_xor_b32_e32 v237, 32, v206
	v_xor_b32_e32 v238, 64, v206
	v_xor_b32_e32 v239, 0x60, v206
	s_branch .LBB0_1195

; DEV void sb_block(const Params& p, int item) {
;     ...
;   for (int n = 0; n < nsteps; ++n) {
;     const int j = nsteps - 1 - n, buf = n & 3;
;     asm volatile("s_waitcnt vmcnt(8)" ::: "memory");
;     __builtin_amdgcn_s_barrier();
;     asm volatile("" ::: "memory");
;     { const int jn = j > 3 ? j - 3 : 0; SB_DMA(jn, (n + 3) & 3); }
;     const char* lb_ = smem + buf * 32768;
;     int ko0 = KO0, vo0 = VO0;
;     asm volatile("" : "+v"(ko0), "+v"(vo0));
;     if (2 * j + 1 == qt) sb_tile<true>(lb_ + 32 * 256, lb_, ko0, vo0 ^ 64, qf, O, accp, l31, hh);
.LBB0_1211:
	s_and_b32 s66, s33, 0x18000
	s_add_i32 s92, s66, 0
	v_add_u32_e32 v240, s92, v228
	v_add_u32_e32 v241, s92, v229
	v_add_u32_e32 v242, s92, v230
	v_add_u32_e32 v243, s92, v231
	v_add_u32_e32 v244, s92, v232
	v_add_u32_e32 v245, s92, v233
	v_add_u32_e32 v246, s92, v234
	v_add_u32_e32 v247, s92, v235
	v_add_u32_e32 v248, s92, v236
	v_add_u32_e32 v249, s92, v237
	v_add_u32_e32 v250, s92, v238
	v_add_u32_e32 v251, s92, v239
	s_add_i32 s90, s74, s69
	v_mov_b32_e32 v168, v205
	v_mov_b32_e32 v193, v206
	s_cmp_lg_u32 s89, s69
	s_mov_b64 s[66:67], -1
	s_cbranch_scc0 .LBB0_1215
	s_add_i32 s66, s90, 7
	s_cmp_ge_i32 s66, s76
	s_cbranch_scc1 .Lsb_skip_A1
; DEV f32x16 mfma32(bf16x8 a, bf16x8 b, f32x16 c) { return __builtin_amdgcn_mfma_f32_32x32x16_bf16(a, b, c, 0, 0, 0); }
; template <bool DIAG>
; DEV void sb_tile(const char* lk, const char* lv, const int ko0, const int vo0, const bf16x8 (&qf)[8], f32x16 (&O)[4], float& accp,
;                  const int l31, const int hh) {
;   f32x16 z;
;   for (int g = 0; g < 16; ++g) z[g] = 0.f;
;   {
;     bf16x8 kf[8];
; #pragma unroll
;     for (int s = 0; s < 8; ++s) kf[s] = *(const bf16x8*)(lk + (ko0 ^ (32 * s)));
;     __builtin_amdgcn_sched_barrier(0);
; #pragma unroll
;     for (int s = 0; s < 8; ++s) z = mfma32(kf[s], qf[s], z);
;   }
;   bf16x8 vf[4][2];
; #pragma unroll
;   for (int d = 0; d < 4; ++d) { vf[d][0] = *(const bf16x8*)(lv + d * 4096 + vo0); vf[d][1] = *(const bf16x8*)(lv + d * 4096 + (vo0 ^ 32)); }
;   __builtin_amdgcn_sched_barrier(0);
;   float be[16], om[16];
; #pragma unroll
;   for (int g = 0; g < 16; ++g) {
;     const float e = __builtin_amdgcn_exp2f(fminf(-z[g], 120.f));
;     be[g] = __builtin_amdgcn_rcpf(1.f + e);
;     om[g] = e * be[g];
;     if (DIAG) { const int kl = (g & 3) + 8 * (g >> 2) + 4 * hh; if (kl >= l31) { be[g] = 0.f; om[g] = 1.f; } }
;   }
;   float gp[4], pp[4], tot[4];
; #pragma unroll
;   for (int q = 0; q < 4; ++q) { gp[q] = (om[4 * q] * om[4 * q + 1]) * (om[4 * q + 2] * om[4 * q + 3]); pp[q] = __shfl_xor(gp[q], 32); tot[q] = gp[q] * pp[q]; }
;   float suf[4];
;   suf[3] = accp; suf[2] = suf[3] * tot[3]; suf[1] = suf[2] * tot[2]; suf[0] = suf[1] * tot[1];
;   accp = suf[0] * tot[0];
;   f32x16 w;
; #pragma unroll
;   for (int q = 0; q < 4; ++q) {
;     float a = suf[q] * (hh == 0 ? pp[q] : 1.f);
;     w[4 * q + 3] = be[4 * q + 3] * a; a *= om[4 * q + 3];
;     w[4 * q + 2] = be[4 * q + 2] * a; a *= om[4 * q + 2];
;     w[4 * q + 1] = be[4 * q + 1] * a; a *= om[4 * q + 1];
;     w[4 * q + 0] = be[4 * q + 0] * a;
;   }
;   const bf16x8 w0 = cvt8<0>(w), w1 = cvt8<1>(w);
; #pragma unroll
;   for (int d = 0; d < 4; ++d) { O[d] = mfma32(vf[d][0], w0, O[d]); O[d] = mfma32(vf[d][1], w1, O[d]); }
; DEV void sb_block(const Params& p, int item) {
;     ...
;     if (2 * j + 1 == qt) sb_tile<true>(lb_ + 32 * 256, lb_, ko0, vo0 ^ 64, qf, O, accp, l31, hh);
;     else if (2 * j + 1 < qt) sb_tile<false>(lb_ + 32 * 256, lb_, ko0, vo0 ^ 64, qf, O, accp, l31, hh);
	ds_read_b128 v[64:67], v240 offset:8192
	ds_read_b128 v[80:83], v241 offset:8192
	ds_read_b128 v[84:87], v242 offset:8192
	ds_read_b128 v[88:91], v243 offset:8192
	ds_read_b128 v[92:95], v244 offset:8192
	ds_read_b128 v[96:99], v245 offset:8192
	ds_read_b128 v[100:103], v246 offset:8192
	ds_read_b128 v[104:107], v247 offset:8192
	s_waitcnt lgkmcnt(0)
	v_mfma_f32_32x32x16_bf16 v[64:79], v[64:67], v[128:131], 0
	v_mfma_f32_32x32x16_bf16 v[64:79], v[80:83], v[132:135], v[64:79]
	v_mfma_f32_32x32x16_bf16 v[64:79], v[84:87], v[136:139], v[64:79]
	v_mfma_f32_32x32x16_bf16 v[64:79], v[88:91], v[140:143], v[64:79]
	v_mfma_f32_32x32x16_bf16 v[64:79], v[92:95], v[144:147], v[64:79]
	v_mfma_f32_32x32x16_bf16 v[64:79], v[96:99], v[148:151], v[64:79]
	v_mfma_f32_32x32x16_bf16 v[64:79], v[100:103], v[152:155], v[64:79]
	ds_read_b128 v[84:87], v250
	ds_read_b128 v[96:99], v250 offset:4096
	ds_read_b128 v[80:83], v251
	ds_read_b128 v[100:103], v251 offset:4096
	ds_read_b128 v[112:115], v250 offset:8192
	ds_read_b128 v[164:167], v250 offset:12288
	ds_read_b128 v[116:119], v251 offset:8192
	ds_read_b128 v[160:163], v251 offset:12288
	v_mfma_f32_32x32x16_bf16 v[64:79], v[104:107], v[156:159], v[64:79]
	s_nop 11
	v_min_f32_e64 v68, -v68, s32
	v_exp_f32_e32 v90, v68
	v_min_f32_e64 v68, -v69, s32
	v_exp_f32_e32 v91, v68
	v_add_f32_e32 v68, 1.0, v90
	v_min_f32_e64 v73, -v73, s32
	v_add_f32_e32 v69, 1.0, v91
	v_rcp_f32_e32 v68, v68
	v_rcp_f32_e32 v69, v69
	v_exp_f32_e32 v104, v73
	v_max_f32_e64 v73, -v74, -v74
	v_max_f32_e64 v74, -v75, -v75
	v_min_f32_e64 v72, -v72, s32
	v_min_f32_e32 v74, 0x42f00000, v74
	v_min_f32_e64 v75, -v77, s32
	v_max_f32_e64 v77, -v79, -v79
	v_and_b32_e32 v79, 64, v219
	v_exp_f32_e32 v72, v72
	v_exp_f32_e32 v105, v74
	v_max_f32_e64 v74, -v76, -v76
	v_exp_f32_e32 v76, v75
	v_max_f32_e64 v75, -v78, -v78
	v_xor_b32_e32 v78, 32, v219
	v_add_u32_e32 v79, 64, v79
	v_min_f32_e32 v73, 0x42f00000, v73
	v_cmp_lt_i32_e32 vcc, v78, v79
	v_pk_mul_f32 v[90:91], v[90:91], v[68:69]
	v_exp_f32_e32 v73, v73
	v_cndmask_b32_e32 v78, v219, v78, vcc
	v_lshlrev_b32_e32 v170, 2, v78
	v_pk_mul_f32 v[78:79], v[90:91], v[90:91] op_sel_hi:[0,1]
	v_add_f32_e32 v78, 1.0, v72
	v_rcp_f32_e32 v108, v78
	v_add_f32_e32 v78, 1.0, v104
	v_rcp_f32_e32 v110, v78
	v_add_f32_e32 v78, 1.0, v73
	v_rcp_f32_e32 v109, v78
	v_add_f32_e32 v78, 1.0, v105
	v_min_f32_e32 v74, 0x42f00000, v74
	v_rcp_f32_e32 v111, v78
	v_exp_f32_e32 v74, v74
	v_min_f32_e32 v75, 0x42f00000, v75
	v_exp_f32_e32 v75, v75
	v_min_f32_e32 v77, 0x42f00000, v77
	v_exp_f32_e32 v77, v77
	v_pk_mul_f32 v[72:73], v[72:73], v[108:109]
	v_pk_mul_f32 v[104:105], v[104:105], v[110:111]
	v_pk_mul_f32 v[120:121], v[72:73], v[104:105]
	v_add_f32_e32 v72, 1.0, v74
	v_rcp_f32_e32 v122, v72
	v_add_f32_e32 v72, 1.0, v76
	v_rcp_f32_e32 v124, v72
	v_add_f32_e32 v72, 1.0, v75
	v_min_f32_e64 v70, -v70, s32
	v_rcp_f32_e32 v123, v72
	v_add_f32_e32 v72, 1.0, v77
	v_exp_f32_e32 v92, v70
	v_rcp_f32_e32 v125, v72
	v_min_f32_e64 v70, -v71, s32
	v_min_f32_e64 v67, -v67, s32
	v_exp_f32_e32 v93, v70
	v_min_f32_e64 v64, -v64, s32
	v_exp_f32_e32 v196, v67
	v_exp_f32_e32 v88, v64
	v_pk_mul_f32 v[74:75], v[74:75], v[122:123]
	v_pk_mul_f32 v[76:77], v[76:77], v[124:125]
	v_add_f32_e32 v70, 1.0, v92
	v_pk_mul_f32 v[126:127], v[74:75], v[76:77]
	v_add_f32_e32 v71, 1.0, v93
	v_mul_f32_e32 v72, v126, v127
	v_add_f32_e32 v67, 1.0, v196
	v_rcp_f32_e32 v70, v70
	v_rcp_f32_e32 v71, v71
	v_pk_mul_f32 v[120:121], v[120:121], v[120:121] op_sel:[0,1] op_sel_hi:[1,0]
	v_mov_b32_e32 v74, v72
	s_nop 1
	v_permlane32_swap_b32_e32 v72, v74
	v_add_f32_e32 v64, 1.0, v88
	v_min_f32_e64 v66, -v66, s32
	v_rcp_f32_e32 v67, v67
	v_mov_b32_e32 v121, v120
	s_nop 1
	v_permlane32_swap_b32_e32 v120, v121
	v_rcp_f32_e32 v64, v64
	v_min_f32_e64 v65, -v65, s32
	v_exp_f32_e32 v94, v66
	v_exp_f32_e32 v169, v65
	v_pk_mul_f32 v[92:93], v[92:93], v[70:71]
	s_waitcnt lgkmcnt(0)
	v_mul_f32_e32 v127, v72, v74
	v_pk_mul_f32 v[106:107], v[92:93], v[92:93] op_sel_hi:[0,1]
	v_mov_b32_e32 v126, v67
	v_add_f32_e32 v66, 1.0, v94
	v_mov_b32_e32 v89, v79
	v_cndmask_b32_e64 v72, 1.0, v121, s[10:11]
	v_mov_b32_e32 v78, v109
	v_mov_b32_e32 v79, v111
	v_mov_b32_e32 v109, v110
	v_pk_mul_f32 v[110:111], v[196:197], v[126:127]
	v_mov_b32_e32 v106, v64
	v_add_f32_e32 v65, 1.0, v169
	v_rcp_f32_e32 v66, v66
	v_mul_f32_e32 v127, v72, v111
	v_pk_mul_f32 v[88:89], v[88:89], v[106:107]
	v_rcp_f32_e32 v65, v65
	v_mul_f32_e32 v126, v105, v127
	v_mov_b32_e32 v105, v89
	s_nop 1
	v_permlane32_swap_b32_e32 v89, v105
	v_mov_b32_e32 v95, v120
	v_mov_b32_e32 v120, v66
	v_mul_f32_e32 v73, v73, v126
	v_pk_mul_f32 v[94:95], v[94:95], v[120:121]
	v_mul_f32_e32 v72, v104, v73
	v_mul_f32_e32 v104, v169, v65
	v_pk_mul_f32 v[120:121], v[94:95], v[110:111]
	s_waitcnt lgkmcnt(0)
	v_pk_mul_f32 v[88:89], v[88:89], v[104:105]
	v_cndmask_b32_e64 v90, 1.0, v105, s[10:11]
	v_pk_mul_f32 v[88:89], v[88:89], v[120:121]
	v_mov_b32_e32 v95, v88
	s_nop 1
	v_permlane32_swap_b32_e32 v88, v95
	v_cndmask_b32_e64 v74, 1.0, v74, s[10:11]
	v_pk_mul_f32 v[78:79], v[78:79], v[126:127]
	v_pk_mul_f32 v[72:73], v[108:109], v[72:73]
	v_cvt_pk_bf16_f32 v209, v78, v79
	s_waitcnt lgkmcnt(0)
	v_mul_f32_e32 v88, v88, v95
	v_mul_f32_e32 v199, v88, v89
	v_cndmask_b32_e64 v88, 1.0, v95, s[10:11]
	v_mul_f32_e32 v89, v88, v89
	v_mul_f32_e32 v88, v110, v89
	v_pk_mul_f32 v[66:67], v[66:67], v[88:89]
	v_mul_f32_e32 v89, v90, v121
	v_mul_f32_e32 v95, v94, v88
	v_mul_f32_e32 v88, v93, v89
	v_mul_f32_e32 v93, v92, v88
	v_mul_f32_e32 v92, v91, v93
	v_mul_f32_e32 v91, v197, v74
	v_mul_f32_e32 v90, v77, v91
	v_mul_f32_e32 v94, v104, v95
	v_mul_f32_e32 v75, v75, v90
	v_pk_mul_f32 v[64:65], v[64:65], v[94:95]
	v_pk_mul_f32 v[68:69], v[68:69], v[92:93]
	v_pk_mul_f32 v[70:71], v[70:71], v[88:89]
	v_mov_b32_e32 v88, v123
	v_mov_b32_e32 v123, v124
	v_mul_f32_e32 v74, v76, v75
	v_pk_mul_f32 v[74:75], v[122:123], v[74:75]
	v_cvt_pk_bf16_f32 v170, v64, v65
	v_cvt_pk_bf16_f32 v171, v66, v67
	v_cvt_pk_bf16_f32 v172, v68, v69
	v_cvt_pk_bf16_f32 v173, v70, v71
	v_cvt_pk_bf16_f32 v208, v72, v73
	v_cvt_pk_bf16_f32 v210, v74, v75
	v_mfma_f32_32x32x16_bf16 v[64:79], v[84:87], v[170:173], v[48:63]
	v_mov_b32_e32 v89, v125
	v_mul_f32_e64 v88, v88, v90
	v_mul_f32_e64 v89, v89, v91
	v_cvt_pk_bf16_f32 v211, v88, v89
	s_nop 1
	v_mfma_f32_32x32x16_bf16 v[64:79], v[80:83], v[208:211], v[64:79]
	v_mfma_f32_32x32x16_bf16 v[80:95], v[96:99], v[170:173], v[32:47]
	v_mfma_f32_32x32x16_bf16 v[80:95], v[100:103], v[208:211], v[80:95]
	v_mfma_f32_32x32x16_bf16 v[96:111], v[112:115], v[170:173], v[16:31]
	v_mfma_f32_32x32x16_bf16 v[96:111], v[116:119], v[208:211], v[96:111]
	v_mfma_f32_32x32x16_bf16 v[112:127], v[164:167], v[170:173], v[0:15]
	v_mfma_f32_32x32x16_bf16 v[112:127], v[160:163], v[208:211], v[112:127]

; DEV f32x16 mfma32(bf16x8 a, bf16x8 b, f32x16 c) { return __builtin_amdgcn_mfma_f32_32x32x16_bf16(a, b, c, 0, 0, 0); }
; template <bool DIAG>
; DEV void sb_tile(const char* lk, const char* lv, const int ko0, const int vo0, const bf16x8 (&qf)[8], f32x16 (&O)[4], float& accp,
;                  const int l31, const int hh) {
;   f32x16 z;
;   for (int g = 0; g < 16; ++g) z[g] = 0.f;
;   {
;     bf16x8 kf[8];
; #pragma unroll
;     for (int s = 0; s < 8; ++s) kf[s] = *(const bf16x8*)(lk + (ko0 ^ (32 * s)));
;     __builtin_amdgcn_sched_barrier(0);
; #pragma unroll
;     for (int s = 0; s < 8; ++s) z = mfma32(kf[s], qf[s], z);
;   }
;   bf16x8 vf[4][2];
; #pragma unroll
;   for (int d = 0; d < 4; ++d) { vf[d][0] = *(const bf16x8*)(lv + d * 4096 + vo0); vf[d][1] = *(const bf16x8*)(lv + d * 4096 + (vo0 ^ 32)); }
;   __builtin_amdgcn_sched_barrier(0);
;   float be[16], om[16];
; #pragma unroll
;   for (int g = 0; g < 16; ++g) {
;     const float e = __builtin_amdgcn_exp2f(fminf(-z[g], 120.f));
;     be[g] = __builtin_amdgcn_rcpf(1.f + e);
;     om[g] = e * be[g];
;     if (DIAG) { const int kl = (g & 3) + 8 * (g >> 2) + 4 * hh; if (kl >= l31) { be[g] = 0.f; om[g] = 1.f; } }
;   }
;   float gp[4], pp[4], tot[4];
; #pragma unroll
;   for (int q = 0; q < 4; ++q) { gp[q] = (om[4 * q] * om[4 * q + 1]) * (om[4 * q + 2] * om[4 * q + 3]); pp[q] = __shfl_xor(gp[q], 32); tot[q] = gp[q] * pp[q]; }
;   float suf[4];
;   suf[3] = accp; suf[2] = suf[3] * tot[3]; suf[1] = suf[2] * tot[2]; suf[0] = suf[1] * tot[1];
;   accp = suf[0] * tot[0];
;   f32x16 w;
; #pragma unroll
;   for (int q = 0; q < 4; ++q) {
;     float a = suf[q] * (hh == 0 ? pp[q] : 1.f);
;     w[4 * q + 3] = be[4 * q + 3] * a; a *= om[4 * q + 3];
;     w[4 * q + 2] = be[4 * q + 2] * a; a *= om[4 * q + 2];
;     w[4 * q + 1] = be[4 * q + 1] * a; a *= om[4 * q + 1];
;     w[4 * q + 0] = be[4 * q + 0] * a;
;   }
;   const bf16x8 w0 = cvt8<0>(w), w1 = cvt8<1>(w);
; #pragma unroll
;   for (int d = 0; d < 4; ++d) { O[d] = mfma32(vf[d][0], w0, O[d]); O[d] = mfma32(vf[d][1], w1, O[d]); }
; DEV void sb_block(const Params& p, int item) {
;     ...
;     if (2 * j == qt) sb_tile<true>(lb_, lb_, ko0, vo0, qf, O, accp, l31, hh);
;     else if (2 * j < qt) sb_tile<false>(lb_, lb_, ko0, vo0, qf, O, accp, l31, hh);
.LBB0_1217:
	s_cmp_lg_u32 s88, s69
	s_mov_b64 s[66:67], -1
	s_cbranch_scc0 .LBB0_1221
	s_add_i32 s90, s90, 6
	s_cmp_ge_i32 s90, s76
	s_cbranch_scc1 .Lsb_skip_B1
	ds_read_b128 v[0:3], v240
	ds_read_b128 v[16:19], v241
	ds_read_b128 v[20:23], v242
	ds_read_b128 v[24:27], v243
	ds_read_b128 v[28:31], v244
	ds_read_b128 v[32:35], v245
	ds_read_b128 v[36:39], v246
	ds_read_b128 v[40:43], v247
	s_waitcnt lgkmcnt(0)
	v_mfma_f32_32x32x16_bf16 v[0:15], v[0:3], v[128:131], 0
	v_mfma_f32_32x32x16_bf16 v[0:15], v[16:19], v[132:135], v[0:15]
	v_mfma_f32_32x32x16_bf16 v[0:15], v[20:23], v[136:139], v[0:15]
	v_mfma_f32_32x32x16_bf16 v[0:15], v[24:27], v[140:143], v[0:15]
	v_mfma_f32_32x32x16_bf16 v[0:15], v[28:31], v[144:147], v[0:15]
	v_mfma_f32_32x32x16_bf16 v[0:15], v[32:35], v[148:151], v[0:15]
	ds_read_b128 v[28:31], v248
	ds_read_b128 v[16:19], v248 offset:4096
	ds_read_b128 v[24:27], v249
	ds_read_b128 v[20:23], v249 offset:4096
	ds_read_b128 v[168:171], v248 offset:8192
	ds_read_b128 v[164:167], v248 offset:12288
	ds_read_b128 v[172:175], v249 offset:8192
	ds_read_b128 v[160:163], v249 offset:12288
	v_mfma_f32_32x32x16_bf16 v[0:15], v[36:39], v[152:155], v[0:15]
	v_mfma_f32_32x32x16_bf16 v[0:15], v[40:43], v[156:159], v[0:15]
	s_nop 11
	v_min_f32_e64 v4, -v4, s32
	v_exp_f32_e32 v34, v4
	v_min_f32_e64 v4, -v5, s32
	v_exp_f32_e32 v35, v4
	v_add_f32_e32 v4, 1.0, v34
	v_min_f32_e64 v9, -v9, s32
	v_add_f32_e32 v5, 1.0, v35
	v_rcp_f32_e32 v4, v4
	v_rcp_f32_e32 v5, v5
	v_exp_f32_e32 v40, v9
	v_max_f32_e64 v9, -v10, -v10
	v_max_f32_e64 v10, -v11, -v11
	v_min_f32_e64 v8, -v8, s32
	v_min_f32_e32 v10, 0x42f00000, v10
	v_min_f32_e64 v11, -v13, s32
	v_max_f32_e64 v13, -v15, -v15
	v_and_b32_e32 v15, 64, v219
	v_exp_f32_e32 v8, v8
	v_exp_f32_e32 v41, v10
	v_max_f32_e64 v10, -v12, -v12
	v_exp_f32_e32 v12, v11
	v_max_f32_e64 v11, -v14, -v14
	v_xor_b32_e32 v14, 32, v219
	v_add_u32_e32 v15, 64, v15
	v_min_f32_e32 v9, 0x42f00000, v9
	v_cmp_lt_i32_e32 vcc, v14, v15
	v_pk_mul_f32 v[34:35], v[34:35], v[4:5]
	v_exp_f32_e32 v9, v9
	v_cndmask_b32_e32 v14, v219, v14, vcc
	v_lshlrev_b32_e32 v57, 2, v14
	v_pk_mul_f32 v[14:15], v[34:35], v[34:35] op_sel_hi:[0,1]
	v_add_f32_e32 v14, 1.0, v8
	v_rcp_f32_e32 v44, v14
	v_add_f32_e32 v14, 1.0, v40
	v_rcp_f32_e32 v46, v14
	v_add_f32_e32 v14, 1.0, v9
	v_rcp_f32_e32 v45, v14
	v_add_f32_e32 v14, 1.0, v41
	v_min_f32_e32 v10, 0x42f00000, v10
	v_rcp_f32_e32 v47, v14
	v_exp_f32_e32 v10, v10
	v_min_f32_e32 v11, 0x42f00000, v11
	v_exp_f32_e32 v11, v11
	v_min_f32_e32 v13, 0x42f00000, v13
	v_exp_f32_e32 v13, v13
	v_pk_mul_f32 v[8:9], v[8:9], v[44:45]
	v_pk_mul_f32 v[40:41], v[40:41], v[46:47]
	v_pk_mul_f32 v[48:49], v[8:9], v[40:41]
	v_add_f32_e32 v8, 1.0, v10
	v_rcp_f32_e32 v50, v8
	v_add_f32_e32 v8, 1.0, v12
	v_rcp_f32_e32 v52, v8
	v_add_f32_e32 v8, 1.0, v11
	v_min_f32_e64 v6, -v6, s32
	v_rcp_f32_e32 v51, v8
	v_add_f32_e32 v8, 1.0, v13
	v_exp_f32_e32 v36, v6
	v_rcp_f32_e32 v53, v8
	v_min_f32_e64 v6, -v7, s32
	v_min_f32_e64 v3, -v3, s32
	v_exp_f32_e32 v37, v6
	v_min_f32_e64 v0, -v0, s32
	v_exp_f32_e32 v198, v3
	v_exp_f32_e32 v32, v0
	v_pk_mul_f32 v[10:11], v[10:11], v[50:51]
	v_pk_mul_f32 v[12:13], v[12:13], v[52:53]
	v_add_f32_e32 v6, 1.0, v36
	v_pk_mul_f32 v[54:55], v[10:11], v[12:13]
	v_add_f32_e32 v7, 1.0, v37
	v_mul_f32_e32 v8, v54, v55
	v_add_f32_e32 v3, 1.0, v198
	v_rcp_f32_e32 v6, v6
	v_rcp_f32_e32 v7, v7
	v_pk_mul_f32 v[48:49], v[48:49], v[48:49] op_sel:[0,1] op_sel_hi:[1,0]
	v_mov_b32_e32 v10, v8
	s_nop 1
	v_permlane32_swap_b32_e32 v8, v10
	v_add_f32_e32 v0, 1.0, v32
	v_min_f32_e64 v2, -v2, s32
	v_rcp_f32_e32 v3, v3
	v_mov_b32_e32 v49, v48
	s_nop 1
	v_permlane32_swap_b32_e32 v48, v49
	v_rcp_f32_e32 v0, v0
	v_min_f32_e64 v1, -v1, s32
	v_exp_f32_e32 v38, v2
	v_exp_f32_e32 v56, v1
	v_pk_mul_f32 v[36:37], v[36:37], v[6:7]
	s_waitcnt lgkmcnt(0)
	v_mul_f32_e32 v55, v8, v10
	v_pk_mul_f32 v[42:43], v[36:37], v[36:37] op_sel_hi:[0,1]
	v_mov_b32_e32 v54, v3
	v_add_f32_e32 v2, 1.0, v38
	v_mov_b32_e32 v33, v15
	v_cndmask_b32_e64 v8, 1.0, v49, s[10:11]
	v_mov_b32_e32 v14, v45
	v_mov_b32_e32 v15, v47
	v_mov_b32_e32 v45, v46
	v_pk_mul_f32 v[46:47], v[198:199], v[54:55]
	v_mov_b32_e32 v42, v0
	v_add_f32_e32 v1, 1.0, v56
	v_rcp_f32_e32 v2, v2
	v_mul_f32_e32 v55, v8, v47
	v_pk_mul_f32 v[32:33], v[32:33], v[42:43]
	v_rcp_f32_e32 v1, v1
	v_mul_f32_e32 v54, v41, v55
	v_mov_b32_e32 v41, v33
	s_nop 1
	v_permlane32_swap_b32_e32 v33, v41
	v_mov_b32_e32 v39, v48
	v_mov_b32_e32 v48, v2
	v_mul_f32_e32 v9, v9, v54
	v_pk_mul_f32 v[38:39], v[38:39], v[48:49]
	v_mul_f32_e32 v8, v40, v9
	v_mul_f32_e32 v40, v56, v1
	v_pk_mul_f32 v[48:49], v[38:39], v[46:47]
	s_waitcnt lgkmcnt(0)
	v_pk_mul_f32 v[32:33], v[32:33], v[40:41]
	v_cndmask_b32_e64 v34, 1.0, v41, s[10:11]
	v_pk_mul_f32 v[32:33], v[32:33], v[48:49]
	v_mov_b32_e32 v39, v32
	s_nop 1
	v_permlane32_swap_b32_e32 v32, v39
	v_cndmask_b32_e64 v10, 1.0, v10, s[10:11]
	v_pk_mul_f32 v[14:15], v[14:15], v[54:55]
	v_pk_mul_f32 v[8:9], v[44:45], v[8:9]
	v_cvt_pk_bf16_f32 v225, v14, v15
	s_waitcnt lgkmcnt(0)
	v_mul_f32_e32 v32, v32, v39
	v_mul_f32_e32 v197, v32, v33
	v_cndmask_b32_e64 v32, 1.0, v39, s[10:11]
	v_mul_f32_e32 v33, v32, v33
	v_mul_f32_e32 v32, v46, v33
	v_pk_mul_f32 v[2:3], v[2:3], v[32:33]
	v_mul_f32_e32 v33, v34, v49
	v_mul_f32_e32 v39, v38, v32
	v_mul_f32_e32 v32, v37, v33
	v_mul_f32_e32 v37, v36, v32
	v_mul_f32_e32 v36, v35, v37
	v_mul_f32_e32 v35, v199, v10
	v_mul_f32_e32 v38, v40, v39
	v_mul_f32_e32 v34, v13, v35
	v_pk_mul_f32 v[0:1], v[0:1], v[38:39]
	v_pk_mul_f32 v[4:5], v[4:5], v[36:37]
	v_pk_mul_f32 v[6:7], v[6:7], v[32:33]
	v_mov_b32_e32 v32, v51
	v_mov_b32_e32 v33, v53
	v_mul_f32_e32 v11, v11, v34
	v_pk_mul_f32 v[32:33], v[32:33], v[34:35]
	v_mov_b32_e32 v51, v52
	v_mul_f32_e32 v10, v12, v11
	v_cvt_pk_bf16_f32 v214, v0, v1
	v_cvt_pk_bf16_f32 v215, v2, v3
	v_cvt_pk_bf16_f32 v216, v4, v5
	v_cvt_pk_bf16_f32 v217, v6, v7
	v_pk_mul_f32 v[10:11], v[50:51], v[10:11]
	v_cvt_pk_bf16_f32 v227, v32, v33
	v_mfma_f32_32x32x16_bf16 v[48:63], v[28:31], v[214:217], v[64:79]
	v_cvt_pk_bf16_f32 v224, v8, v9
	v_cvt_pk_bf16_f32 v226, v10, v11
	v_mfma_f32_32x32x16_bf16 v[32:47], v[16:19], v[214:217], v[80:95]
	s_nop 0
	v_mfma_f32_32x32x16_bf16 v[48:63], v[24:27], v[224:227], v[48:63]
	v_mfma_f32_32x32x16_bf16 v[32:47], v[20:23], v[224:227], v[32:47]
	v_mfma_f32_32x32x16_bf16 v[16:31], v[168:171], v[214:217], v[96:111]
	v_mfma_f32_32x32x16_bf16 v[0:15], v[164:167], v[214:217], v[112:127]
	v_mfma_f32_32x32x16_bf16 v[16:31], v[172:175], v[224:227], v[16:31]
	v_mfma_f32_32x32x16_bf16 v[0:15], v[160:163], v[224:227], v[0:15]
